# P3 gelu epilogue: sigmoid argument as v*(A+(Bv)v) with folded f32 constants (3 VALU instead of 6); P4 GLU epilogue: bias add and -log2e scale folded into one fmamk; on top of v123
# speedup vs baseline: 1.0056x; 1.0056x over previous
; #define PG8_STAGE(bufoff, gbase, voff) do { _Pragma("unroll") for (int _i = 0; _i < 2; ++_i) \
;         __builtin_amdgcn_global_load_lds((const unsigned*)((const char*)(gbase) + (voff)[_i]), (PG8_LAS unsigned*)(lds + (bufoff) + ldsw + _i * 8192), 16, 0, 0); } while (0)
; #define PG8_LDA(dst, b, h) do { _Pragma("unroll") for (int m = 0; m < 4; ++m) _Pragma("unroll") for (int k = 0; k < 2; ++k) dst[m][k] = *(const PG8_LAS bf16x8*)(lds + PG8_SA(b, h) + aoff + m * 2048 + k * 1024); } while (0)
; #define PG8_LDB(dst, b, h) do { _Pragma("unroll") for (int n = 0; n < 2; ++n) _Pragma("unroll") for (int k = 0; k < 2; ++k) dst[n][k] = *(const PG8_LAS bf16x8*)(lds + PG8_SB(b, h) + boff + n * 2048 + k * 1024); } while (0)
; #define PG8_WAIT_L(n) asm volatile("s_waitcnt lgkmcnt(" #n ")" ::: "memory")
; #define PG8_BAR __builtin_amdgcn_s_barrier()
; #define PG8_SCHED __builtin_amdgcn_sched_barrier(0)
; template <class Epi, class Sched, bool ALIGN_EPI = false, bool SP2 = false, bool FP8 = false>
; __device__ __forceinline__ void gemm_phase(PG8_LAS unsigned char* lds, const Gemm g, const Sched& S, const Epi& E) {
;     ...
;             PG8_LDB(B0, 0, 0); PG8_SCHED; PG8_LDA(At, 0, 0); PG8_STAGE(PG8_SA(1, 1), a1 + hstepA, voffA);
;             PG8_WAIT_L(8); PG8_BAR; PG8_WAIT_L(0); PG8_MMA(0, 0, At, B0); PG8_BAR; PG8_SCHED;
;             PG8_LDB(B1, 0, 1); PG8_STAGE(PG8_SB(0, 0), b2, voffB);
;             PG8_BAR; PG8_WAIT_L(0); PG8_MMA(0, 1, At, B1); PG8_BAR;
;             PG8_LDA(At, 0, 1); PG8_STAGE(PG8_SA(0, 0), a2, voffA);
;             PG8_BAR; PG8_WAIT_L(0); PG8_MMA(1, 0, At, B0); PG8_BAR; PG8_SCHED;
.LBB0_501:
	s_add_u32 s16, s8, s14
	ds_read_b128 v[150:153], v144
	ds_read_b128 v[154:157], v144 offset:1024
	ds_read_b128 v[158:161], v144 offset:2048
	ds_read_b128 v[166:169], v144 offset:3072
	s_addc_u32 s17, s9, s15
	s_add_u32 s16, s16, 0xe000100
	s_addc_u32 s17, s17, 0
	s_add_u32 s55, s40, s14
	s_addc_u32 s56, s41, s15
	s_cmpk_eq_i32 s14, 0x500
	s_cselect_b32 s19, s3, s17
	s_cselect_b32 s18, s2, s16
	s_cselect_b32 s17, s1, s56
	s_cselect_b32 s16, s0, s55
	s_mov_b32 m0, s43
	v_lshl_add_u64 v[202:203], v[138:139], 0, s[14:15]
	ds_read_b128 v[170:173], v145
	ds_read_b128 v[174:177], v145 offset:1024
	ds_read_b128 v[178:181], v145 offset:2048
	ds_read_b128 v[182:185], v145 offset:3072
	ds_read_b128 v[186:189], v145 offset:4096
	ds_read_b128 v[190:193], v145 offset:5120
	ds_read_b128 v[194:197], v145 offset:6144
	ds_read_b128 v[198:201], v145 offset:7168
	global_load_lds_dwordx4 v[202:203], off
	v_lshl_add_u64 v[202:203], v[140:141], 0, s[14:15]
	s_mov_b32 m0, s44
	s_nop 0
	global_load_lds_dwordx4 v[202:203], off
	s_waitcnt lgkmcnt(8)
	s_barrier
	s_waitcnt lgkmcnt(0)
	s_setprio 1
	s_waitcnt lgkmcnt(0)
	v_mfma_f32_16x16x32_bf16 v[126:129], v[150:153], v[170:173], v[126:129]
	v_mfma_f32_16x16x32_bf16 v[122:125], v[158:161], v[170:173], v[122:125]
	v_mfma_f32_16x16x32_bf16 v[118:121], v[150:153], v[178:181], v[118:121]
	v_mfma_f32_16x16x32_bf16 v[114:117], v[158:161], v[178:181], v[114:117]
	v_mfma_f32_16x16x32_bf16 v[110:113], v[150:153], v[186:189], v[110:113]
	v_mfma_f32_16x16x32_bf16 v[106:109], v[158:161], v[186:189], v[106:109]
	v_mfma_f32_16x16x32_bf16 v[102:105], v[150:153], v[194:197], v[102:105]
	v_mfma_f32_16x16x32_bf16 v[98:101], v[158:161], v[194:197], v[98:101]
	v_mfma_f32_16x16x32_bf16 v[126:129], v[154:157], v[174:177], v[126:129]
	v_mfma_f32_16x16x32_bf16 v[122:125], v[166:169], v[174:177], v[122:125]
	v_mfma_f32_16x16x32_bf16 v[118:121], v[154:157], v[182:185], v[118:121]
	v_mfma_f32_16x16x32_bf16 v[114:117], v[166:169], v[182:185], v[114:117]
	v_mfma_f32_16x16x32_bf16 v[110:113], v[154:157], v[190:193], v[110:113]
	v_mfma_f32_16x16x32_bf16 v[106:109], v[166:169], v[190:193], v[106:109]
	v_mfma_f32_16x16x32_bf16 v[102:105], v[154:157], v[198:201], v[102:105]
	v_mfma_f32_16x16x32_bf16 v[98:101], v[166:169], v[198:201], v[98:101]
	s_setprio 0
	s_barrier
	s_mov_b32 m0, s45
	v_lshl_add_u64 v[218:219], s[16:17], 0, v[134:135]
	ds_read_b128 v[202:205], v146
	ds_read_b128 v[206:209], v146 offset:1024
	ds_read_b128 v[210:213], v146 offset:2048
	ds_read_b128 v[214:217], v146 offset:3072
	global_load_lds_dwordx4 v[218:219], off
	v_lshl_add_u64 v[220:221], s[16:17], 0, v[130:131]
	s_mov_b32 m0, s46
	s_nop 0
	global_load_lds_dwordx4 v[220:221], off
	s_barrier
	s_waitcnt lgkmcnt(0)
	s_setprio 1
	s_waitcnt lgkmcnt(0)
	v_mfma_f32_16x16x32_bf16 v[62:65], v[202:205], v[170:173], v[62:65]
	v_mfma_f32_16x16x32_bf16 v[58:61], v[210:213], v[170:173], v[58:61]
	v_mfma_f32_16x16x32_bf16 v[54:57], v[202:205], v[178:181], v[54:57]
	v_mfma_f32_16x16x32_bf16 v[50:53], v[210:213], v[178:181], v[50:53]
	v_mfma_f32_16x16x32_bf16 v[46:49], v[202:205], v[186:189], v[46:49]
	v_mfma_f32_16x16x32_bf16 v[42:45], v[210:213], v[186:189], v[42:45]
	v_mfma_f32_16x16x32_bf16 v[38:41], v[202:205], v[194:197], v[38:41]
	v_mfma_f32_16x16x32_bf16 v[34:37], v[210:213], v[194:197], v[34:37]
	v_mfma_f32_16x16x32_bf16 v[62:65], v[206:209], v[174:177], v[62:65]
	v_mfma_f32_16x16x32_bf16 v[58:61], v[214:217], v[174:177], v[58:61]
	v_mfma_f32_16x16x32_bf16 v[54:57], v[206:209], v[182:185], v[54:57]
	v_mfma_f32_16x16x32_bf16 v[50:53], v[214:217], v[182:185], v[50:53]
	v_mfma_f32_16x16x32_bf16 v[46:49], v[206:209], v[190:193], v[46:49]
	v_mfma_f32_16x16x32_bf16 v[42:45], v[214:217], v[190:193], v[42:45]
	v_mfma_f32_16x16x32_bf16 v[38:41], v[206:209], v[198:201], v[38:41]
	v_mfma_f32_16x16x32_bf16 v[34:37], v[214:217], v[198:201], v[34:37]
	s_setprio 0
	s_mov_b32 m0, s11
	v_lshl_add_u64 v[222:223], s[18:19], 0, v[136:137]
	s_barrier
	ds_read_b128 v[170:173], v145 offset:16384
	ds_read_b128 v[174:177], v145 offset:17408
	ds_read_b128 v[178:181], v145 offset:18432
	ds_read_b128 v[182:185], v145 offset:19456
	ds_read_b128 v[186:189], v145 offset:20480
	ds_read_b128 v[190:193], v145 offset:21504
	ds_read_b128 v[194:197], v145 offset:22528
	ds_read_b128 v[198:201], v145 offset:23552
	global_load_lds_dwordx4 v[222:223], off
	v_lshl_add_u64 v[224:225], s[18:19], 0, v[132:133]
	s_mov_b32 m0, s26
	s_nop 0
	global_load_lds_dwordx4 v[224:225], off
	s_barrier
	s_waitcnt lgkmcnt(0)
	s_setprio 1
	s_waitcnt lgkmcnt(0)
	v_mfma_f32_16x16x32_bf16 v[94:97], v[150:153], v[170:173], v[94:97]
	v_mfma_f32_16x16x32_bf16 v[90:93], v[158:161], v[170:173], v[90:93]
	v_mfma_f32_16x16x32_bf16 v[86:89], v[150:153], v[178:181], v[86:89]
	v_mfma_f32_16x16x32_bf16 v[82:85], v[158:161], v[178:181], v[82:85]
	v_mfma_f32_16x16x32_bf16 v[78:81], v[150:153], v[186:189], v[78:81]
	v_mfma_f32_16x16x32_bf16 v[74:77], v[158:161], v[186:189], v[74:77]
	v_mfma_f32_16x16x32_bf16 v[70:73], v[150:153], v[194:197], v[70:73]
	v_mfma_f32_16x16x32_bf16 v[66:69], v[158:161], v[194:197], v[66:69]
	v_mfma_f32_16x16x32_bf16 v[94:97], v[154:157], v[174:177], v[94:97]
	v_mfma_f32_16x16x32_bf16 v[90:93], v[166:169], v[174:177], v[90:93]
	v_mfma_f32_16x16x32_bf16 v[86:89], v[154:157], v[182:185], v[86:89]
	v_mfma_f32_16x16x32_bf16 v[82:85], v[166:169], v[182:185], v[82:85]
	v_mfma_f32_16x16x32_bf16 v[78:81], v[154:157], v[190:193], v[78:81]
	v_mfma_f32_16x16x32_bf16 v[74:77], v[166:169], v[190:193], v[74:77]
	v_mfma_f32_16x16x32_bf16 v[70:73], v[154:157], v[198:201], v[70:73]
	v_mfma_f32_16x16x32_bf16 v[66:69], v[166:169], v[198:201], v[66:69]
	s_setprio 0
	s_barrier
; #define PG8_STAGE(bufoff, gbase, voff) do { _Pragma("unroll") for (int _i = 0; _i < 2; ++_i) \
;         __builtin_amdgcn_global_load_lds((const unsigned*)((const char*)(gbase) + (voff)[_i]), (PG8_LAS unsigned*)(lds + (bufoff) + ldsw + _i * 8192), 16, 0, 0); } while (0)
; #define PG8_LDA(dst, b, h) do { _Pragma("unroll") for (int m = 0; m < 4; ++m) _Pragma("unroll") for (int k = 0; k < 2; ++k) dst[m][k] = *(const PG8_LAS bf16x8*)(lds + PG8_SA(b, h) + aoff + m * 2048 + k * 1024); } while (0)
; #define PG8_LDB(dst, b, h) do { _Pragma("unroll") for (int n = 0; n < 2; ++n) _Pragma("unroll") for (int k = 0; k < 2; ++k) dst[n][k] = *(const PG8_LAS bf16x8*)(lds + PG8_SB(b, h) + boff + n * 2048 + k * 1024); } while (0)
; #define PG8_WAIT_V(n) asm volatile("s_waitcnt vmcnt(" #n ")" ::: "memory")
; #define PG8_WAIT_L(n) asm volatile("s_waitcnt lgkmcnt(" #n ")" ::: "memory")
; #define PG8_BAR __builtin_amdgcn_s_barrier()
; #define PG8_SCHED __builtin_amdgcn_sched_barrier(0)
; template <class Epi, class Sched, bool ALIGN_EPI = false, bool SP2 = false, bool FP8 = false>
; __device__ __forceinline__ void gemm_phase(PG8_LAS unsigned char* lds, const Gemm g, const Sched& S, const Epi& E) {
;     ...
;             PG8_STAGE(PG8_SB(0, 1), b2 + hstepB, voffB);
;             PG8_WAIT_V(6); PG8_BAR; PG8_MMA(1, 1, At, B1); PG8_BAR;
;             PG8_LDB(B0, 1, 0); PG8_SCHED; PG8_LDA(At, 1, 0); PG8_STAGE(PG8_SA(0, 1), a2 + hstepA, voffA);
;             PG8_WAIT_L(8); PG8_BAR; PG8_WAIT_L(0); PG8_MMA(0, 0, At, B0); PG8_BAR; PG8_SCHED;
;             PG8_LDB(B1, 1, 1); PG8_STAGE(PG8_SB(1, 0), b3, voffB);
;             PG8_BAR; PG8_WAIT_L(0); PG8_MMA(0, 1, At, B1); PG8_BAR;
;             PG8_LDA(At, 1, 1); PG8_STAGE(PG8_SA(1, 0), a3, voffA);
	s_add_u32 s56, s16, 0x30000
	s_addc_u32 s57, s17, 0
	s_mov_b32 m0, s47
	v_lshl_add_u64 v[150:151], s[56:57], 0, v[134:135]
	global_load_lds_dwordx4 v[150:151], off
	v_lshl_add_u64 v[150:151], s[56:57], 0, v[130:131]
	s_mov_b32 m0, s48
	s_nop 0
	global_load_lds_dwordx4 v[150:151], off
	s_waitcnt vmcnt(6)
	s_barrier
	s_setprio 1
	v_mfma_f32_16x16x32_bf16 v[30:33], v[202:205], v[170:173], v[30:33]
	v_mfma_f32_16x16x32_bf16 v[26:29], v[210:213], v[170:173], v[26:29]
	v_mfma_f32_16x16x32_bf16 v[22:25], v[202:205], v[178:181], v[22:25]
	v_mfma_f32_16x16x32_bf16 v[18:21], v[210:213], v[178:181], v[18:21]
	v_mfma_f32_16x16x32_bf16 v[14:17], v[202:205], v[186:189], v[14:17]
	v_mfma_f32_16x16x32_bf16 v[10:13], v[210:213], v[186:189], v[10:13]
	v_mfma_f32_16x16x32_bf16 v[6:9], v[202:205], v[194:197], v[6:9]
	v_mfma_f32_16x16x32_bf16 v[2:5], v[210:213], v[194:197], v[2:5]
	v_mfma_f32_16x16x32_bf16 v[30:33], v[206:209], v[174:177], v[30:33]
	v_mfma_f32_16x16x32_bf16 v[26:29], v[214:217], v[174:177], v[26:29]
	v_mfma_f32_16x16x32_bf16 v[22:25], v[206:209], v[182:185], v[22:25]
	v_mfma_f32_16x16x32_bf16 v[18:21], v[214:217], v[182:185], v[18:21]
	v_mfma_f32_16x16x32_bf16 v[14:17], v[206:209], v[190:193], v[14:17]
	v_mfma_f32_16x16x32_bf16 v[10:13], v[214:217], v[190:193], v[10:13]
	v_mfma_f32_16x16x32_bf16 v[6:9], v[206:209], v[198:201], v[6:9]
	v_mfma_f32_16x16x32_bf16 v[2:5], v[214:217], v[198:201], v[2:5]
	s_setprio 0
	s_barrier
	ds_read_b128 v[150:153], v147
	ds_read_b128 v[154:157], v147 offset:1024
	ds_read_b128 v[158:161], v147 offset:2048
	ds_read_b128 v[166:169], v147 offset:3072
	s_add_u32 s18, s18, 0x30000
	s_addc_u32 s19, s19, 0
	s_mov_b32 m0, s33
	v_lshl_add_u64 v[202:203], s[18:19], 0, v[136:137]
	ds_read_b128 v[170:173], v145 offset:32768
	ds_read_b128 v[174:177], v145 offset:33792
	ds_read_b128 v[178:181], v145 offset:34816
	ds_read_b128 v[182:185], v145 offset:35840
	ds_read_b128 v[186:189], v145 offset:36864
	ds_read_b128 v[190:193], v145 offset:37888
	ds_read_b128 v[194:197], v145 offset:38912
	ds_read_b128 v[198:201], v145 offset:39936
	global_load_lds_dwordx4 v[202:203], off
	v_lshl_add_u64 v[202:203], s[18:19], 0, v[132:133]
	s_mov_b32 m0, s36
	s_nop 0
	global_load_lds_dwordx4 v[202:203], off
	s_waitcnt lgkmcnt(8)
	s_barrier
	s_waitcnt lgkmcnt(0)
	s_setprio 1
	s_waitcnt lgkmcnt(0)
	v_mfma_f32_16x16x32_bf16 v[126:129], v[150:153], v[170:173], v[126:129]
	v_mfma_f32_16x16x32_bf16 v[122:125], v[158:161], v[170:173], v[122:125]
	v_mfma_f32_16x16x32_bf16 v[118:121], v[150:153], v[178:181], v[118:121]
	v_mfma_f32_16x16x32_bf16 v[114:117], v[158:161], v[178:181], v[114:117]
	v_mfma_f32_16x16x32_bf16 v[110:113], v[150:153], v[186:189], v[110:113]
	v_mfma_f32_16x16x32_bf16 v[106:109], v[158:161], v[186:189], v[106:109]
	v_mfma_f32_16x16x32_bf16 v[102:105], v[150:153], v[194:197], v[102:105]
	v_mfma_f32_16x16x32_bf16 v[98:101], v[158:161], v[194:197], v[98:101]
	v_mfma_f32_16x16x32_bf16 v[126:129], v[154:157], v[174:177], v[126:129]
	v_mfma_f32_16x16x32_bf16 v[122:125], v[166:169], v[174:177], v[122:125]
	v_mfma_f32_16x16x32_bf16 v[118:121], v[154:157], v[182:185], v[118:121]
	v_mfma_f32_16x16x32_bf16 v[114:117], v[166:169], v[182:185], v[114:117]
	v_mfma_f32_16x16x32_bf16 v[110:113], v[154:157], v[190:193], v[110:113]
	v_mfma_f32_16x16x32_bf16 v[106:109], v[166:169], v[190:193], v[106:109]
	v_mfma_f32_16x16x32_bf16 v[102:105], v[154:157], v[198:201], v[102:105]
	v_mfma_f32_16x16x32_bf16 v[98:101], v[166:169], v[198:201], v[98:101]
	s_setprio 0
	s_barrier
	s_mov_b32 m0, s49
	v_lshl_add_u64 v[218:219], v[218:219], 0, s[4:5]
	ds_read_b128 v[202:205], v148
	ds_read_b128 v[206:209], v148 offset:1024
	ds_read_b128 v[210:213], v148 offset:2048
	ds_read_b128 v[214:217], v148 offset:3072
	global_load_lds_dwordx4 v[218:219], off
	v_lshl_add_u64 v[218:219], v[220:221], 0, s[4:5]
	s_mov_b32 m0, s52
	s_nop 0
	global_load_lds_dwordx4 v[218:219], off
	s_barrier
	s_waitcnt lgkmcnt(0)
	s_setprio 1
	s_waitcnt lgkmcnt(0)
	v_mfma_f32_16x16x32_bf16 v[62:65], v[202:205], v[170:173], v[62:65]
	v_mfma_f32_16x16x32_bf16 v[58:61], v[210:213], v[170:173], v[58:61]
	v_mfma_f32_16x16x32_bf16 v[54:57], v[202:205], v[178:181], v[54:57]
	v_mfma_f32_16x16x32_bf16 v[50:53], v[210:213], v[178:181], v[50:53]
	v_mfma_f32_16x16x32_bf16 v[46:49], v[202:205], v[186:189], v[46:49]
	v_mfma_f32_16x16x32_bf16 v[42:45], v[210:213], v[186:189], v[42:45]
	v_mfma_f32_16x16x32_bf16 v[38:41], v[202:205], v[194:197], v[38:41]
	v_mfma_f32_16x16x32_bf16 v[34:37], v[210:213], v[194:197], v[34:37]
	v_mfma_f32_16x16x32_bf16 v[62:65], v[206:209], v[174:177], v[62:65]
	v_mfma_f32_16x16x32_bf16 v[58:61], v[214:217], v[174:177], v[58:61]
	v_mfma_f32_16x16x32_bf16 v[54:57], v[206:209], v[182:185], v[54:57]
	v_mfma_f32_16x16x32_bf16 v[50:53], v[214:217], v[182:185], v[50:53]
	v_mfma_f32_16x16x32_bf16 v[46:49], v[206:209], v[190:193], v[46:49]
	v_mfma_f32_16x16x32_bf16 v[42:45], v[214:217], v[190:193], v[42:45]
	v_mfma_f32_16x16x32_bf16 v[38:41], v[206:209], v[198:201], v[38:41]
	v_mfma_f32_16x16x32_bf16 v[34:37], v[214:217], v[198:201], v[34:37]
	s_setprio 0
	s_mov_b32 m0, s38
	v_lshl_add_u64 v[218:219], v[222:223], 0, s[4:5]
	s_barrier
	ds_read_b128 v[170:173], v145 offset:49152
	ds_read_b128 v[174:177], v145 offset:50176
	ds_read_b128 v[178:181], v145 offset:51200
	ds_read_b128 v[182:185], v145 offset:52224
	ds_read_b128 v[186:189], v145 offset:53248
	ds_read_b128 v[190:193], v145 offset:54272
	ds_read_b128 v[194:197], v145 offset:55296
	ds_read_b128 v[198:201], v145 offset:56320
	global_load_lds_dwordx4 v[218:219], off
	v_lshl_add_u64 v[218:219], v[224:225], 0, s[4:5]
	s_mov_b32 m0, s39
	s_nop 0
	global_load_lds_dwordx4 v[218:219], off
	s_barrier
; __device__ __forceinline__ unsigned cvt_pk_bf16(float lo, float hi) { unsigned r; asm volatile("v_cvt_pk_bf16_f32 %0, %1, %2" : "=v"(r) : "v"(lo), "v"(hi)); return r; }
; #define PG8_STAGE(bufoff, gbase, voff) do { _Pragma("unroll") for (int _i = 0; _i < 2; ++_i) \
;         __builtin_amdgcn_global_load_lds((const unsigned*)((const char*)(gbase) + (voff)[_i]), (PG8_LAS unsigned*)(lds + (bufoff) + ldsw + _i * 8192), 16, 0, 0); } while (0)
; #define PG8_WAIT_V(n) asm volatile("s_waitcnt vmcnt(" #n ")" ::: "memory")
; #define PG8_WAIT_L(n) asm volatile("s_waitcnt lgkmcnt(" #n ")" ::: "memory")
; #define PG8_BAR __builtin_amdgcn_s_barrier()
; #define PG8_SCHED __builtin_amdgcn_sched_barrier(0)
; __device__ __forceinline__ float gelu_t(float v) { const float u = 0.7978845608028654f * (v + 0.044715f * v * v * v); return v * sigm(2.f * u); }
; template <class Epi, class Sched, bool ALIGN_EPI = false, bool SP2 = false, bool FP8 = false>
; __device__ __forceinline__ void gemm_phase(PG8_LAS unsigned char* lds, const Gemm g, const Sched& S, const Epi& E) {
;     ...
;             PG8_BAR; PG8_WAIT_L(0); PG8_MMA(1, 0, At, B0); PG8_BAR; PG8_SCHED;
;             PG8_STAGE(PG8_SB(1, 1), b3 + hstepB, voffB);
;             PG8_WAIT_V(6); PG8_BAR; PG8_MMA(1, 1, At, B1); PG8_BAR;
;             }
;         }
;     __device__ __forceinline__ void operator()(const f32x4 (&acc)[2][2][4][2], const Unit& u, int wr, int wc, int fr, int fq) const {
;     ...
;                     const int row = row0 + ai * 128 + m * 16, b = row >> 6, chunk = row & 63; const size_t tok = (size_t)b * SEQ + chunk * LCH + i;
;                     f32x4 v0 = acc[ai][bj][m][0], v1 = acc[ai][bj][m][1];
; #pragma unroll
;                     for (int j = 0; j < 4; ++j) { v0[j] = gelu_t(v0[j]); v1[j] = gelu_t(v1[j]); }
;                     v4u w; w.x = pg8::cvt_pk_bf16(v0[0], v0[1]); w.y = pg8::cvt_pk_bf16(v0[2], v0[3]); w.z = pg8::cvt_pk_bf16(v1[0], v1[1]); w.w = pg8::cvt_pk_bf16(v1[2], v1[3]);
;                     *(v4u*)(YG + tok * 512 + u.pz * 16 + c0) = w;
	s_waitcnt lgkmcnt(0)
	s_setprio 1
	s_waitcnt lgkmcnt(0)
	v_mfma_f32_16x16x32_bf16 v[94:97], v[150:153], v[170:173], v[94:97]
	v_mfma_f32_16x16x32_bf16 v[90:93], v[158:161], v[170:173], v[90:93]
	v_mfma_f32_16x16x32_bf16 v[86:89], v[150:153], v[178:181], v[86:89]
	v_mfma_f32_16x16x32_bf16 v[82:85], v[158:161], v[178:181], v[82:85]
	v_mfma_f32_16x16x32_bf16 v[78:81], v[150:153], v[186:189], v[78:81]
	v_mfma_f32_16x16x32_bf16 v[74:77], v[158:161], v[186:189], v[74:77]
	v_mfma_f32_16x16x32_bf16 v[70:73], v[150:153], v[194:197], v[70:73]
	v_mfma_f32_16x16x32_bf16 v[66:69], v[158:161], v[194:197], v[66:69]
	v_mfma_f32_16x16x32_bf16 v[94:97], v[154:157], v[174:177], v[94:97]
	v_mfma_f32_16x16x32_bf16 v[90:93], v[166:169], v[174:177], v[90:93]
	v_mfma_f32_16x16x32_bf16 v[86:89], v[154:157], v[182:185], v[86:89]
	v_mfma_f32_16x16x32_bf16 v[82:85], v[166:169], v[182:185], v[82:85]
	v_mfma_f32_16x16x32_bf16 v[78:81], v[154:157], v[190:193], v[78:81]
	v_mfma_f32_16x16x32_bf16 v[74:77], v[166:169], v[190:193], v[74:77]
	v_mfma_f32_16x16x32_bf16 v[70:73], v[154:157], v[198:201], v[70:73]
	v_mfma_f32_16x16x32_bf16 v[66:69], v[166:169], v[198:201], v[66:69]
	s_setprio 0
	s_barrier
	s_add_u32 s16, s16, 0x30080
	s_addc_u32 s17, s17, 0
	s_mov_b32 m0, s53
	v_lshl_add_u64 v[150:151], s[16:17], 0, v[134:135]
	global_load_lds_dwordx4 v[150:151], off
	v_lshl_add_u64 v[150:151], s[16:17], 0, v[130:131]
	s_mov_b32 m0, s54
	s_nop 0
	global_load_lds_dwordx4 v[150:151], off
	s_waitcnt vmcnt(6)
	s_barrier
	s_setprio 1
	v_mfma_f32_16x16x32_bf16 v[30:33], v[202:205], v[170:173], v[30:33]
	v_mfma_f32_16x16x32_bf16 v[26:29], v[210:213], v[170:173], v[26:29]
	v_mfma_f32_16x16x32_bf16 v[22:25], v[202:205], v[178:181], v[22:25]
	v_mfma_f32_16x16x32_bf16 v[18:21], v[210:213], v[178:181], v[18:21]
	v_mfma_f32_16x16x32_bf16 v[14:17], v[202:205], v[186:189], v[14:17]
	v_mfma_f32_16x16x32_bf16 v[10:13], v[210:213], v[186:189], v[10:13]
	v_mfma_f32_16x16x32_bf16 v[6:9], v[202:205], v[194:197], v[6:9]
	v_mfma_f32_16x16x32_bf16 v[2:5], v[210:213], v[194:197], v[2:5]
	v_mfma_f32_16x16x32_bf16 v[30:33], v[206:209], v[174:177], v[30:33]
	v_mfma_f32_16x16x32_bf16 v[26:29], v[214:217], v[174:177], v[26:29]
	v_mfma_f32_16x16x32_bf16 v[22:25], v[206:209], v[182:185], v[22:25]
	v_mfma_f32_16x16x32_bf16 v[18:21], v[214:217], v[182:185], v[18:21]
	v_mfma_f32_16x16x32_bf16 v[14:17], v[206:209], v[190:193], v[14:17]
	v_mfma_f32_16x16x32_bf16 v[10:13], v[214:217], v[190:193], v[10:13]
	v_mfma_f32_16x16x32_bf16 v[6:9], v[206:209], v[198:201], v[6:9]
	v_mfma_f32_16x16x32_bf16 v[2:5], v[214:217], v[198:201], v[2:5]
	s_setprio 0
	s_add_i32 s42, s42, 2
	s_add_u32 s14, s14, 0x100
	s_addc_u32 s15, s15, 0
	s_cmp_gt_u32 s42, 9
	s_barrier
	s_cbranch_scc0 .LBB0_501
	v_lshlrev_b32_e32 v136, 5, v142
	v_mul_f32_e32 v138, 0xbdd2d3e7, v126
	v_mul_f32_e32 v142, 0xbdd2d3e7, v122
	v_and_b32_e32 v140, 8, v143
	v_fmaak_f32 v138, v126, v138, 0xc0135761
	v_fmaak_f32 v142, v122, v142, 0xc0135761
	v_mul_f32_e32 v143, 0xbdd2d3e7, v127
	v_mul_f32_e32 v138, v126, v138
	v_mul_f32_e32 v142, v122, v142
	v_fmaak_f32 v143, v127, v143, 0xc0135761
	v_mul_f32_e32 v143, v127, v143
	v_exp_f32_e32 v141, v138
	v_exp_f32_e32 v142, v142
	v_exp_f32_e32 v143, v143
	v_add_f32_e32 v141, 1.0, v141
	v_add_f32_e32 v142, 1.0, v142
	v_mul_f32_e32 v144, 0xbdd2d3e7, v123
	v_rcp_f32_e32 v141, v141
	v_rcp_f32_e32 v142, v142
	v_add_f32_e32 v143, 1.0, v143
	v_fmaak_f32 v144, v123, v144, 0xc0135761
	v_rcp_f32_e32 v143, v143
	v_mul_f32_e32 v144, v123, v144
	v_mul_f32_e32 v126, v126, v141
	v_mul_f32_e32 v141, v122, v142
	v_mul_f32_e32 v142, 0xbdd2d3e7, v128
	v_exp_f32_e32 v144, v144
	v_mul_f32_e32 v127, v127, v143
	v_fmaak_f32 v142, v128, v142, 0xc0135761
	v_mul_f32_e32 v143, 0xbdd2d3e7, v124
	v_mul_f32_e32 v142, v128, v142
	v_fmaak_f32 v143, v124, v143, 0xc0135761
	v_mul_f32_e32 v143, v124, v143
	v_add_f32_e32 v122, 1.0, v144
	v_rcp_f32_e32 v122, v122
	v_exp_f32_e32 v142, v142
	v_exp_f32_e32 v143, v143
	v_mul_f32_e32 v144, v123, v122
	v_add_f32_e32 v122, 1.0, v142
	v_mul_f32_e32 v142, 0xbdd2d3e7, v129
	v_add_f32_e32 v123, 1.0, v143
	v_fmaak_f32 v142, v129, v142, 0xc0135761
	v_mul_f32_e32 v143, 0xbdd2d3e7, v125
	s_ashr_i32 s11, s10, 31
	v_mul_f32_e32 v142, v129, v142
	v_fmaak_f32 v143, v125, v143, 0xc0135761
	s_lshl_b64 s[0:1], s[10:11], 24
	v_mul_f32_e32 v143, v125, v143
	s_add_u32 s0, s30, s0
	s_addc_u32 s1, s31, s1
	s_add_u32 s0, s0, 0x3000000
	v_exp_f32_e32 v142, v142
	s_addc_u32 s1, s1, 0
	s_lshl_b32 s2, s25, 8
	v_exp_f32_e32 v143, v143
	s_add_i32 s8, s27, s2
	v_lshl_or_b32 v1, s24, 8, v1
	s_ashr_i32 s2, s8, 6
	v_rcp_f32_e32 v122, v122
	v_rcp_f32_e32 v123, v123
	v_or_b32_e32 v1, s37, v1
	s_ashr_i32 s3, s2, 31
	v_add_f32_e32 v142, 1.0, v142
	v_lshrrev_b32_e32 v1, 4, v1
	s_lshl_b64 s[4:5], s[2:3], 11
	v_rcp_f32_e32 v142, v142
	v_add_f32_e32 v143, 1.0, v143
	v_mov_b32_e32 v137, 0
	v_or_b32_e32 v138, s4, v1
	v_mov_b32_e32 v139, s5
	v_rcp_f32_e32 v143, v143
	v_mul_f32_e32 v128, v128, v122
	v_mul_f32_e32 v145, v124, v123
	v_lshl_add_u64 v[122:123], v[138:139], 0, v[136:137]
	s_lshl_b32 s2, s23, 4
	v_lshlrev_b64 v[122:123], 10, v[122:123]
	s_ashr_i32 s3, s2, 31
	v_mul_f32_e32 v129, v129, v142
	v_lshl_add_u64 v[122:123], s[0:1], 0, v[122:123]
	s_lshl_b64 s[2:3], s[2:3], 1
	v_mul_f32_e32 v142, v125, v143
	v_cvt_pk_bf16_f32 v124, v126, v127
	v_cvt_pk_bf16_f32 v125, v128, v129
	v_lshl_add_u64 v[128:129], v[122:123], 0, s[2:3]
	v_mul_f32_e32 v123, 0xbdd2d3e7, v118
	v_fmaak_f32 v123, v118, v123, 0xc0135761
	v_mul_f32_e32 v123, v118, v123
	v_lshlrev_b32_e32 v122, 1, v140
	v_exp_f32_e32 v140, v123
	v_mov_b32_e32 v123, v137
	v_cvt_pk_bf16_f32 v126, v141, v144
; __device__ __forceinline__ unsigned cvt_pk_bf16(float lo, float hi) { unsigned r; asm volatile("v_cvt_pk_bf16_f32 %0, %1, %2" : "=v"(r) : "v"(lo), "v"(hi)); return r; }
; __device__ __forceinline__ float gelu_t(float v) { const float u = 0.7978845608028654f * (v + 0.044715f * v * v * v); return v * sigm(2.f * u); }
;     __device__ __forceinline__ void operator()(const f32x4 (&acc)[2][2][4][2], const Unit& u, int wr, int wc, int fr, int fq) const {
;     ...
;                     const int row = row0 + ai * 128 + m * 16, b = row >> 6, chunk = row & 63; const size_t tok = (size_t)b * SEQ + chunk * LCH + i;
;                     f32x4 v0 = acc[ai][bj][m][0], v1 = acc[ai][bj][m][1];
; #pragma unroll
;                     for (int j = 0; j < 4; ++j) { v0[j] = gelu_t(v0[j]); v1[j] = gelu_t(v1[j]); }
;                     v4u w; w.x = pg8::cvt_pk_bf16(v0[0], v0[1]); w.y = pg8::cvt_pk_bf16(v0[2], v0[3]); w.z = pg8::cvt_pk_bf16(v1[0], v1[1]); w.w = pg8::cvt_pk_bf16(v1[2], v1[3]);
;                     *(v4u*)(YG + tok * 512 + u.pz * 16 + c0) = w;
	v_lshl_add_u64 v[128:129], v[128:129], 0, v[122:123]
	v_cvt_pk_bf16_f32 v127, v145, v142
	global_store_dwordx4 v[128:129], v[124:127], off
	v_or_b32_e32 v134, 0x200, v136
	v_mov_b32_e32 v135, v137
	v_mul_f32_e32 v125, 0xbdd2d3e7, v114
	v_mul_f32_e32 v126, 0xbdd2d3e7, v119
	v_fmaak_f32 v125, v114, v125, 0xc0135761
	v_fmaak_f32 v126, v119, v126, 0xc0135761
	v_mul_f32_e32 v125, v114, v125
	v_mul_f32_e32 v126, v119, v126
	v_exp_f32_e32 v125, v125
	v_exp_f32_e32 v126, v126
	v_mul_f32_e32 v127, 0xbdd2d3e7, v115
	v_fmaak_f32 v127, v115, v127, 0xc0135761
	v_add_f32_e32 v125, 1.0, v125
	v_add_f32_e32 v126, 1.0, v126
	v_rcp_f32_e32 v125, v125
	v_rcp_f32_e32 v126, v126
	v_mul_f32_e32 v127, v115, v127
	v_add_f32_e32 v124, 1.0, v140
	v_mul_f32_e32 v125, v114, v125
	v_mul_f32_e32 v114, v119, v126
	v_mul_f32_e32 v119, 0xbdd2d3e7, v120
	v_rcp_f32_e32 v124, v124
	v_exp_f32_e32 v127, v127
	v_fmaak_f32 v119, v120, v119, 0xc0135761
	v_mul_f32_e32 v119, v120, v119
	v_mul_f32_e32 v126, 0xbdd2d3e7, v116
	v_mul_f32_e32 v124, v118, v124
	v_add_f32_e32 v118, 1.0, v127
	v_fmaak_f32 v126, v116, v126, 0xc0135761
	v_rcp_f32_e32 v118, v118
	v_exp_f32_e32 v119, v119
	v_mul_f32_e32 v126, v116, v126
	v_exp_f32_e32 v126, v126
	v_mul_f32_e32 v127, v115, v118
	v_add_f32_e32 v115, 1.0, v119
	v_mul_f32_e32 v119, 0xbdd2d3e7, v121
	v_fmaak_f32 v119, v121, v119, 0xc0135761
	v_mul_f32_e32 v119, v121, v119
	v_add_f32_e32 v118, 1.0, v126
	v_mul_f32_e32 v126, 0xbdd2d3e7, v117
	v_fmaak_f32 v126, v117, v126, 0xc0135761
	v_exp_f32_e32 v119, v119
	v_mul_f32_e32 v126, v117, v126
	v_exp_f32_e32 v126, v126
	v_add_f32_e32 v119, 1.0, v119
	v_rcp_f32_e32 v115, v115
	v_rcp_f32_e32 v118, v118
	v_rcp_f32_e32 v119, v119
	v_add_f32_e32 v126, 1.0, v126
	v_rcp_f32_e32 v126, v126
	v_mul_f32_e32 v115, v120, v115
	v_mul_f32_e32 v120, v116, v118
	v_mul_f32_e32 v116, v121, v119
	v_lshl_add_u64 v[118:119], v[138:139], 0, v[134:135]
	v_lshlrev_b64 v[118:119], 10, v[118:119]
	v_lshl_add_u64 v[118:119], s[0:1], 0, v[118:119]
	v_lshl_add_u64 v[118:119], v[118:119], 0, s[2:3]
	v_mul_f32_e32 v117, v117, v126
	v_cvt_pk_bf16_f32 v114, v124, v114
	v_cvt_pk_bf16_f32 v115, v115, v116
	v_cvt_pk_bf16_f32 v116, v125, v127
	v_lshl_add_u64 v[118:119], v[118:119], 0, v[122:123]
	v_cvt_pk_bf16_f32 v117, v120, v117
	global_store_dwordx4 v[118:119], v[114:117], off
	v_mul_f32_e32 v120, 0xbdd2d3e7, v110
	v_fmaak_f32 v120, v110, v120, 0xc0135761
	v_mul_f32_e32 v115, 0xbdd2d3e7, v106
	v_mul_f32_e32 v116, 0xbdd2d3e7, v111
	v_fmaak_f32 v115, v106, v115, 0xc0135761
	v_fmaak_f32 v116, v111, v116, 0xc0135761
	v_mul_f32_e32 v115, v106, v115
	v_mul_f32_e32 v116, v111, v116
	v_exp_f32_e32 v115, v115
	v_exp_f32_e32 v116, v116
	v_mul_f32_e32 v120, v110, v120
	v_add_f32_e32 v115, 1.0, v115
	v_add_f32_e32 v116, 1.0, v116
	v_mul_f32_e32 v117, 0xbdd2d3e7, v107
	v_exp_f32_e32 v120, v120
	v_rcp_f32_e32 v115, v115
	v_rcp_f32_e32 v116, v116
	v_fmaak_f32 v117, v107, v117, 0xc0135761
	v_mul_f32_e32 v117, v107, v117
	v_add_f32_e32 v114, 1.0, v120
	v_mul_f32_e32 v115, v106, v115
	v_mul_f32_e32 v106, v111, v116
	v_mul_f32_e32 v111, 0xbdd2d3e7, v112
	v_rcp_f32_e32 v114, v114
	v_exp_f32_e32 v117, v117
	v_fmaak_f32 v111, v112, v111, 0xc0135761
	v_mul_f32_e32 v111, v112, v111
	v_mul_f32_e32 v116, 0xbdd2d3e7, v108
	v_mul_f32_e32 v114, v110, v114
	v_add_f32_e32 v110, 1.0, v117
	v_fmaak_f32 v116, v108, v116, 0xc0135761
	v_rcp_f32_e32 v110, v110
	v_exp_f32_e32 v111, v111
	v_mul_f32_e32 v116, v108, v116
	v_exp_f32_e32 v116, v116
	v_mul_f32_e32 v117, v107, v110
	v_add_f32_e32 v107, 1.0, v111
	v_mul_f32_e32 v111, 0xbdd2d3e7, v113
	v_fmaak_f32 v111, v113, v111, 0xc0135761
	v_mul_f32_e32 v111, v113, v111
	v_add_f32_e32 v110, 1.0, v116
	v_mul_f32_e32 v116, 0xbdd2d3e7, v109
	v_fmaak_f32 v116, v109, v116, 0xc0135761
	v_exp_f32_e32 v111, v111
	v_mul_f32_e32 v116, v109, v116
	v_exp_f32_e32 v116, v116
	v_add_f32_e32 v111, 1.0, v111
	v_rcp_f32_e32 v107, v107
	v_rcp_f32_e32 v110, v110
	v_rcp_f32_e32 v111, v111
	v_or_b32_e32 v132, 0x400, v136
	v_mov_b32_e32 v133, v137
	v_add_f32_e32 v116, 1.0, v116
	v_rcp_f32_e32 v116, v116
	v_mul_f32_e32 v107, v112, v107
	v_mul_f32_e32 v112, v108, v110
	v_mul_f32_e32 v108, v113, v111
	v_lshl_add_u64 v[110:111], v[138:139], 0, v[132:133]
	v_lshlrev_b64 v[110:111], 10, v[110:111]
	v_lshl_add_u64 v[110:111], s[0:1], 0, v[110:111]
	v_lshl_add_u64 v[110:111], v[110:111], 0, s[2:3]
	v_mul_f32_e32 v109, v109, v116
	v_cvt_pk_bf16_f32 v106, v114, v106
	v_cvt_pk_bf16_f32 v107, v107, v108
	v_cvt_pk_bf16_f32 v108, v115, v117
	v_lshl_add_u64 v[110:111], v[110:111], 0, v[122:123]
	v_cvt_pk_bf16_f32 v109, v112, v109
	global_store_dwordx4 v[110:111], v[106:109], off
	v_mul_f32_e32 v112, 0xbdd2d3e7, v102
	v_fmaak_f32 v112, v102, v112, 0xc0135761
	v_mul_f32_e32 v107, 0xbdd2d3e7, v98
	v_mul_f32_e32 v108, 0xbdd2d3e7, v103
	v_fmaak_f32 v107, v98, v107, 0xc0135761
	v_fmaak_f32 v108, v103, v108, 0xc0135761
	v_mul_f32_e32 v107, v98, v107
	v_mul_f32_e32 v108, v103, v108
	v_exp_f32_e32 v107, v107
	v_exp_f32_e32 v108, v108
	v_mul_f32_e32 v112, v102, v112
	v_add_f32_e32 v107, 1.0, v107
	v_add_f32_e32 v108, 1.0, v108
	v_mul_f32_e32 v109, 0xbdd2d3e7, v99
	v_exp_f32_e32 v112, v112
	v_rcp_f32_e32 v107, v107
	v_rcp_f32_e32 v108, v108
	v_fmaak_f32 v109, v99, v109, 0xc0135761
	v_mul_f32_e32 v109, v99, v109
	v_add_f32_e32 v106, 1.0, v112
	v_mul_f32_e32 v107, v98, v107
	v_mul_f32_e32 v98, v103, v108
	v_mul_f32_e32 v103, 0xbdd2d3e7, v104
	v_rcp_f32_e32 v106, v106
	v_exp_f32_e32 v109, v109
	v_fmaak_f32 v103, v104, v103, 0xc0135761
	v_mul_f32_e32 v103, v104, v103
	v_mul_f32_e32 v108, 0xbdd2d3e7, v100
	v_fmaak_f32 v108, v100, v108, 0xc0135761
	v_mul_f32_e32 v106, v102, v106
; __device__ __forceinline__ unsigned cvt_pk_bf16(float lo, float hi) { unsigned r; asm volatile("v_cvt_pk_bf16_f32 %0, %1, %2" : "=v"(r) : "v"(lo), "v"(hi)); return r; }
; __device__ __forceinline__ float fexp2(float x) { return __builtin_amdgcn_exp2f(x); }
; __device__ __forceinline__ float frcp(float x) { return __builtin_amdgcn_rcpf(x); }
; __device__ __forceinline__ float gelu_t(float v) { const float u = 0.7978845608028654f * (v + 0.044715f * v * v * v); return v * sigm(2.f * u); }
; __device__ __forceinline__ float sigm(float v) { return frcp(1.f + fexp2(-LOG2E * v)); }
; __device__ __forceinline__ float silu(float v) { return v * sigm(v); }
;     __device__ __forceinline__ void operator()(const f32x4 (&acc)[2][2][4][2], const Unit& u, int wr, int wc, int fr, int fq) const {
;     ...
;         for (int bj = 0; bj < 2; ++bj) {
;             const int n = u.pn * 256 + bj * 128 + c8, i = n >> 4, c0 = n & 15;
; #pragma unroll
;             for (int ai = 0; ai < 2; ++ai)
; #pragma unroll
;                 for (int m = 0; m < 4; ++m) {
;                     const int row = row0 + ai * 128 + m * 16, b = row >> 6, chunk = row & 63; const size_t tok = (size_t)b * SEQ + chunk * LCH + i;
;                     f32x4 v0 = acc[ai][bj][m][0], v1 = acc[ai][bj][m][1];
; #pragma unroll
;                     for (int j = 0; j < 4; ++j) { v0[j] = gelu_t(v0[j]); v1[j] = gelu_t(v1[j]); }
;                     v4u w; w.x = pg8::cvt_pk_bf16(v0[0], v0[1]); w.y = pg8::cvt_pk_bf16(v0[2], v0[3]); w.z = pg8::cvt_pk_bf16(v1[0], v1[1]); w.w = pg8::cvt_pk_bf16(v1[2], v1[3]);
;                     *(v4u*)(YG + tok * 512 + u.pz * 16 + c0) = w;
;                 }
;         }
	v_add_f32_e32 v102, 1.0, v109
	v_mul_f32_e32 v108, v100, v108
	v_rcp_f32_e32 v102, v102
	v_exp_f32_e32 v103, v103
	v_exp_f32_e32 v108, v108
	v_mul_f32_e32 v109, v99, v102
	v_add_f32_e32 v99, 1.0, v103
	v_mul_f32_e32 v103, 0xbdd2d3e7, v105
	v_fmaak_f32 v103, v105, v103, 0xc0135761
	v_mul_f32_e32 v103, v105, v103
	v_add_f32_e32 v102, 1.0, v108
	v_mul_f32_e32 v108, 0xbdd2d3e7, v101
	v_fmaak_f32 v108, v101, v108, 0xc0135761
	v_mul_f32_e32 v108, v101, v108
	v_exp_f32_e32 v103, v103
	v_exp_f32_e32 v108, v108
	v_add_f32_e32 v103, 1.0, v103
	v_rcp_f32_e32 v99, v99
	v_rcp_f32_e32 v102, v102
	v_rcp_f32_e32 v103, v103
	v_add_f32_e32 v108, 1.0, v108
	v_or_b32_e32 v130, 0x600, v136
	v_mov_b32_e32 v131, v137
	v_rcp_f32_e32 v108, v108
	v_mul_f32_e32 v99, v104, v99
	v_mul_f32_e32 v104, v100, v102
	v_mul_f32_e32 v100, v105, v103
	v_lshl_add_u64 v[102:103], v[138:139], 0, v[130:131]
	v_lshlrev_b64 v[102:103], 10, v[102:103]
	v_lshl_add_u64 v[102:103], s[0:1], 0, v[102:103]
	v_mul_f32_e32 v101, v101, v108
	v_lshl_add_u64 v[102:103], v[102:103], 0, s[2:3]
	v_cvt_pk_bf16_f32 v98, v106, v98
	v_cvt_pk_bf16_f32 v99, v99, v100
	v_cvt_pk_bf16_f32 v100, v107, v109
	v_cvt_pk_bf16_f32 v101, v104, v101
	v_lshl_add_u64 v[102:103], v[102:103], 0, v[122:123]
	global_store_dwordx4 v[102:103], v[98:101], off
	v_mul_f32_e32 v102, 0xbdd2d3e7, v95
	v_fmaak_f32 v102, v95, v102, 0xc0135761
	v_mul_f32_e32 v101, 0xbdd2d3e7, v90
	v_fmaak_f32 v101, v90, v101, 0xc0135761
	v_mul_f32_e32 v101, v90, v101
	v_mul_f32_e32 v102, v95, v102
	v_mul_f32_e32 v98, 0xbdd2d3e7, v94
	v_fmaak_f32 v98, v94, v98, 0xc0135761
	v_exp_f32_e32 v101, v101
	v_exp_f32_e32 v102, v102
	v_mul_f32_e32 v98, v94, v98
	v_add_f32_e32 v101, 1.0, v101
	v_add_f32_e32 v102, 1.0, v102
	v_mul_f32_e32 v103, 0xbdd2d3e7, v91
	v_exp_f32_e32 v100, v98
	v_rcp_f32_e32 v101, v101
	v_rcp_f32_e32 v102, v102
	v_fmaak_f32 v103, v91, v103, 0xc0135761
	v_mul_f32_e32 v103, v91, v103
	v_add_f32_e32 v100, 1.0, v100
	v_mul_f32_e32 v101, v90, v101
	v_mul_f32_e32 v90, v95, v102
	v_mul_f32_e32 v95, 0xbdd2d3e7, v96
	v_rcp_f32_e32 v100, v100
	v_exp_f32_e32 v103, v103
	v_fmaak_f32 v95, v96, v95, 0xc0135761
	v_mul_f32_e32 v95, v96, v95
	v_mul_f32_e32 v102, 0xbdd2d3e7, v92
	v_mul_f32_e32 v100, v94, v100
	v_add_f32_e32 v94, 1.0, v103
	v_fmaak_f32 v102, v92, v102, 0xc0135761
	v_rcp_f32_e32 v94, v94
	v_exp_f32_e32 v95, v95
	v_mul_f32_e32 v102, v92, v102
	v_exp_f32_e32 v102, v102
	v_mul_f32_e32 v103, v91, v94
	v_add_f32_e32 v91, 1.0, v95
	v_mul_f32_e32 v95, 0xbdd2d3e7, v97
	v_fmaak_f32 v95, v97, v95, 0xc0135761
	v_mul_f32_e32 v95, v97, v95
	v_add_f32_e32 v94, 1.0, v102
	v_mul_f32_e32 v102, 0xbdd2d3e7, v93
	v_fmaak_f32 v102, v93, v102, 0xc0135761
	v_exp_f32_e32 v95, v95
	v_mul_f32_e32 v102, v93, v102
	s_addk_i32 s8, 0x80
	v_exp_f32_e32 v102, v102
	v_add_f32_e32 v95, 1.0, v95
	s_ashr_i32 s8, s8, 6
	v_rcp_f32_e32 v91, v91
	v_rcp_f32_e32 v94, v94
	v_rcp_f32_e32 v95, v95
	s_ashr_i32 s9, s8, 31
	s_lshl_b64 s[8:9], s[8:9], 11
	v_or_b32_e32 v98, s8, v1
	v_mov_b32_e32 v99, s9
	v_add_f32_e32 v102, 1.0, v102
	v_rcp_f32_e32 v102, v102
	v_mul_f32_e32 v91, v96, v91
	v_mul_f32_e32 v96, v92, v94
	v_mul_f32_e32 v92, v97, v95
	v_lshl_add_u64 v[94:95], v[98:99], 0, v[136:137]
	v_lshlrev_b64 v[94:95], 10, v[94:95]
	v_lshl_add_u64 v[94:95], s[0:1], 0, v[94:95]
	v_lshl_add_u64 v[94:95], v[94:95], 0, s[2:3]
	v_mul_f32_e32 v93, v93, v102
	v_cvt_pk_bf16_f32 v90, v100, v90
	v_cvt_pk_bf16_f32 v91, v91, v92
	v_cvt_pk_bf16_f32 v92, v101, v103
	v_lshl_add_u64 v[94:95], v[94:95], 0, v[122:123]
	v_cvt_pk_bf16_f32 v93, v96, v93
	global_store_dwordx4 v[94:95], v[90:93], off
	v_mul_f32_e32 v96, 0xbdd2d3e7, v86
	v_fmaak_f32 v96, v86, v96, 0xc0135761
	v_mul_f32_e32 v91, 0xbdd2d3e7, v82
	v_mul_f32_e32 v92, 0xbdd2d3e7, v87
	v_fmaak_f32 v91, v82, v91, 0xc0135761
	v_fmaak_f32 v92, v87, v92, 0xc0135761
	v_mul_f32_e32 v91, v82, v91
	v_mul_f32_e32 v92, v87, v92
	v_exp_f32_e32 v91, v91
	v_exp_f32_e32 v92, v92
	v_mul_f32_e32 v96, v86, v96
	v_add_f32_e32 v91, 1.0, v91
	v_add_f32_e32 v92, 1.0, v92
	v_mul_f32_e32 v93, 0xbdd2d3e7, v83
	v_exp_f32_e32 v96, v96
	v_rcp_f32_e32 v91, v91
	v_rcp_f32_e32 v92, v92
	v_fmaak_f32 v93, v83, v93, 0xc0135761
	v_mul_f32_e32 v93, v83, v93
	v_add_f32_e32 v90, 1.0, v96
	v_mul_f32_e32 v91, v82, v91
	v_mul_f32_e32 v82, v87, v92
	v_mul_f32_e32 v87, 0xbdd2d3e7, v88
	v_rcp_f32_e32 v90, v90
	v_exp_f32_e32 v93, v93
	v_fmaak_f32 v87, v88, v87, 0xc0135761
	v_mul_f32_e32 v87, v88, v87
	v_mul_f32_e32 v92, 0xbdd2d3e7, v84
	v_mul_f32_e32 v90, v86, v90
	v_add_f32_e32 v86, 1.0, v93
	v_fmaak_f32 v92, v84, v92, 0xc0135761
	v_rcp_f32_e32 v86, v86
	v_exp_f32_e32 v87, v87
	v_mul_f32_e32 v92, v84, v92
	v_exp_f32_e32 v92, v92
	v_mul_f32_e32 v93, v83, v86
	v_add_f32_e32 v83, 1.0, v87
	v_mul_f32_e32 v87, 0xbdd2d3e7, v89
	v_fmaak_f32 v87, v89, v87, 0xc0135761
	v_mul_f32_e32 v87, v89, v87
	v_add_f32_e32 v86, 1.0, v92
	v_mul_f32_e32 v92, 0xbdd2d3e7, v85
	v_fmaak_f32 v92, v85, v92, 0xc0135761
	v_exp_f32_e32 v87, v87
	v_mul_f32_e32 v92, v85, v92
	v_exp_f32_e32 v92, v92
	v_add_f32_e32 v87, 1.0, v87
	v_rcp_f32_e32 v83, v83
	v_rcp_f32_e32 v86, v86
	v_rcp_f32_e32 v87, v87
	v_add_f32_e32 v92, 1.0, v92
	v_rcp_f32_e32 v92, v92
	v_mul_f32_e32 v83, v88, v83
	v_mul_f32_e32 v88, v84, v86
	v_mul_f32_e32 v84, v89, v87
	v_lshl_add_u64 v[86:87], v[98:99], 0, v[134:135]
	v_lshlrev_b64 v[86:87], 10, v[86:87]
	v_lshl_add_u64 v[86:87], s[0:1], 0, v[86:87]
	v_lshl_add_u64 v[86:87], v[86:87], 0, s[2:3]
	v_mul_f32_e32 v85, v85, v92
	v_cvt_pk_bf16_f32 v82, v90, v82
	v_cvt_pk_bf16_f32 v83, v83, v84
	v_cvt_pk_bf16_f32 v84, v91, v93
	v_lshl_add_u64 v[86:87], v[86:87], 0, v[122:123]
	v_cvt_pk_bf16_f32 v85, v88, v85
; __device__ __forceinline__ unsigned cvt_pk_bf16(float lo, float hi) { unsigned r; asm volatile("v_cvt_pk_bf16_f32 %0, %1, %2" : "=v"(r) : "v"(lo), "v"(hi)); return r; }
; __device__ __forceinline__ float fexp2(float x) { return __builtin_amdgcn_exp2f(x); }
; __device__ __forceinline__ float frcp(float x) { return __builtin_amdgcn_rcpf(x); }
; __device__ __forceinline__ float gelu_t(float v) { const float u = 0.7978845608028654f * (v + 0.044715f * v * v * v); return v * sigm(2.f * u); }
; __device__ __forceinline__ float sigm(float v) { return frcp(1.f + fexp2(-LOG2E * v)); }
; __device__ __forceinline__ float silu(float v) { return v * sigm(v); }
;     __device__ __forceinline__ void operator()(const f32x4 (&acc)[2][2][4][2], const Unit& u, int wr, int wc, int fr, int fq) const {
;     ...
;         for (int bj = 0; bj < 2; ++bj) {
;             const int n = u.pn * 256 + bj * 128 + c8, i = n >> 4, c0 = n & 15;
; #pragma unroll
;             for (int ai = 0; ai < 2; ++ai)
; #pragma unroll
;                 for (int m = 0; m < 4; ++m) {
;                     const int row = row0 + ai * 128 + m * 16, b = row >> 6, chunk = row & 63; const size_t tok = (size_t)b * SEQ + chunk * LCH + i;
;                     f32x4 v0 = acc[ai][bj][m][0], v1 = acc[ai][bj][m][1];
; #pragma unroll
;                     for (int j = 0; j < 4; ++j) { v0[j] = gelu_t(v0[j]); v1[j] = gelu_t(v1[j]); }
;                     v4u w; w.x = pg8::cvt_pk_bf16(v0[0], v0[1]); w.y = pg8::cvt_pk_bf16(v0[2], v0[3]); w.z = pg8::cvt_pk_bf16(v1[0], v1[1]); w.w = pg8::cvt_pk_bf16(v1[2], v1[3]);
;                     *(v4u*)(YG + tok * 512 + u.pz * 16 + c0) = w;
;                 }
;         }
	global_store_dwordx4 v[86:87], v[82:85], off
	v_mul_f32_e32 v88, 0xbdd2d3e7, v78
	v_fmaak_f32 v88, v78, v88, 0xc0135761
	v_mul_f32_e32 v83, 0xbdd2d3e7, v74
	v_mul_f32_e32 v84, 0xbdd2d3e7, v79
	v_fmaak_f32 v83, v74, v83, 0xc0135761
	v_fmaak_f32 v84, v79, v84, 0xc0135761
	v_mul_f32_e32 v83, v74, v83
	v_mul_f32_e32 v84, v79, v84
	v_exp_f32_e32 v83, v83
	v_exp_f32_e32 v84, v84
	v_mul_f32_e32 v88, v78, v88
	v_add_f32_e32 v83, 1.0, v83
	v_add_f32_e32 v84, 1.0, v84
	v_mul_f32_e32 v85, 0xbdd2d3e7, v75
	v_exp_f32_e32 v88, v88
	v_rcp_f32_e32 v83, v83
	v_rcp_f32_e32 v84, v84
	v_fmaak_f32 v85, v75, v85, 0xc0135761
	v_mul_f32_e32 v85, v75, v85
	v_add_f32_e32 v82, 1.0, v88
	v_mul_f32_e32 v83, v74, v83
	v_mul_f32_e32 v74, v79, v84
	v_mul_f32_e32 v79, 0xbdd2d3e7, v80
	v_rcp_f32_e32 v82, v82
	v_exp_f32_e32 v85, v85
	v_fmaak_f32 v79, v80, v79, 0xc0135761
	v_mul_f32_e32 v79, v80, v79
	v_mul_f32_e32 v84, 0xbdd2d3e7, v76
	v_mul_f32_e32 v82, v78, v82
	v_add_f32_e32 v78, 1.0, v85
	v_fmaak_f32 v84, v76, v84, 0xc0135761
	v_rcp_f32_e32 v78, v78
	v_exp_f32_e32 v79, v79
	v_mul_f32_e32 v84, v76, v84
	v_exp_f32_e32 v84, v84
	v_mul_f32_e32 v85, v75, v78
	v_add_f32_e32 v75, 1.0, v79
	v_mul_f32_e32 v79, 0xbdd2d3e7, v81
	v_fmaak_f32 v79, v81, v79, 0xc0135761
	v_mul_f32_e32 v79, v81, v79
	v_add_f32_e32 v78, 1.0, v84
	v_mul_f32_e32 v84, 0xbdd2d3e7, v77
	v_fmaak_f32 v84, v77, v84, 0xc0135761
	v_exp_f32_e32 v79, v79
	v_mul_f32_e32 v84, v77, v84
	v_exp_f32_e32 v84, v84
	v_add_f32_e32 v79, 1.0, v79
	v_rcp_f32_e32 v75, v75
	v_rcp_f32_e32 v78, v78
	v_rcp_f32_e32 v79, v79
	v_add_f32_e32 v84, 1.0, v84
	v_rcp_f32_e32 v84, v84
	v_mul_f32_e32 v75, v80, v75
	v_mul_f32_e32 v80, v76, v78
	v_mul_f32_e32 v76, v81, v79
	v_lshl_add_u64 v[78:79], v[98:99], 0, v[132:133]
	v_lshlrev_b64 v[78:79], 10, v[78:79]
	v_lshl_add_u64 v[78:79], s[0:1], 0, v[78:79]
	v_lshl_add_u64 v[78:79], v[78:79], 0, s[2:3]
	v_mul_f32_e32 v77, v77, v84
	v_cvt_pk_bf16_f32 v74, v82, v74
	v_cvt_pk_bf16_f32 v75, v75, v76
	v_cvt_pk_bf16_f32 v76, v83, v85
	v_lshl_add_u64 v[78:79], v[78:79], 0, v[122:123]
	v_cvt_pk_bf16_f32 v77, v80, v77
	global_store_dwordx4 v[78:79], v[74:77], off
	v_mul_f32_e32 v80, 0xbdd2d3e7, v70
	v_fmaak_f32 v80, v70, v80, 0xc0135761
	v_mul_f32_e32 v75, 0xbdd2d3e7, v66
	v_mul_f32_e32 v76, 0xbdd2d3e7, v71
	v_fmaak_f32 v75, v66, v75, 0xc0135761
	v_fmaak_f32 v76, v71, v76, 0xc0135761
	v_mul_f32_e32 v75, v66, v75
	v_mul_f32_e32 v76, v71, v76
	v_exp_f32_e32 v75, v75
	v_exp_f32_e32 v76, v76
	v_mul_f32_e32 v80, v70, v80
	v_add_f32_e32 v75, 1.0, v75
	v_add_f32_e32 v76, 1.0, v76
	v_mul_f32_e32 v77, 0xbdd2d3e7, v67
	v_exp_f32_e32 v80, v80
	v_rcp_f32_e32 v75, v75
	v_rcp_f32_e32 v76, v76
	v_fmaak_f32 v77, v67, v77, 0xc0135761
	v_mul_f32_e32 v77, v67, v77
	v_add_f32_e32 v74, 1.0, v80
	v_mul_f32_e32 v75, v66, v75
	v_mul_f32_e32 v66, v71, v76
	v_mul_f32_e32 v71, 0xbdd2d3e7, v72
	v_rcp_f32_e32 v74, v74
	v_exp_f32_e32 v77, v77
	v_fmaak_f32 v71, v72, v71, 0xc0135761
	v_mul_f32_e32 v71, v72, v71
	v_mul_f32_e32 v76, 0xbdd2d3e7, v68
	v_mul_f32_e32 v74, v70, v74
	v_add_f32_e32 v70, 1.0, v77
	v_fmaak_f32 v76, v68, v76, 0xc0135761
	v_rcp_f32_e32 v70, v70
	v_exp_f32_e32 v71, v71
	v_mul_f32_e32 v76, v68, v76
	v_exp_f32_e32 v76, v76
	v_mul_f32_e32 v77, v67, v70
	v_add_f32_e32 v67, 1.0, v71
	v_mul_f32_e32 v71, 0xbdd2d3e7, v73
	v_fmaak_f32 v71, v73, v71, 0xc0135761
	v_mul_f32_e32 v71, v73, v71
	v_add_f32_e32 v70, 1.0, v76
	v_mul_f32_e32 v76, 0xbdd2d3e7, v69
	v_fmaak_f32 v76, v69, v76, 0xc0135761
	v_exp_f32_e32 v71, v71
	v_mul_f32_e32 v76, v69, v76
	v_exp_f32_e32 v76, v76
	v_add_f32_e32 v71, 1.0, v71
	v_rcp_f32_e32 v67, v67
	v_rcp_f32_e32 v70, v70
	v_rcp_f32_e32 v71, v71
	v_add_f32_e32 v76, 1.0, v76
	v_rcp_f32_e32 v76, v76
	v_mul_f32_e32 v67, v72, v67
	v_mul_f32_e32 v72, v68, v70
	v_mul_f32_e32 v68, v73, v71
	v_lshl_add_u64 v[70:71], v[98:99], 0, v[130:131]
	v_lshlrev_b64 v[70:71], 10, v[70:71]
	v_lshl_add_u64 v[70:71], s[0:1], 0, v[70:71]
	v_lshl_add_u64 v[70:71], v[70:71], 0, s[2:3]
	v_mul_f32_e32 v69, v69, v76
	v_cvt_pk_bf16_f32 v66, v74, v66
	v_lshl_add_u64 v[70:71], v[70:71], 0, v[122:123]
	v_cvt_pk_bf16_f32 v67, v67, v68
	v_cvt_pk_bf16_f32 v68, v75, v77
	v_cvt_pk_bf16_f32 v69, v72, v69
	global_store_dwordx4 v[70:71], v[66:69], off
	v_mul_f32_e32 v71, 0xbdd2d3e7, v63
	v_fmaak_f32 v71, v63, v71, 0xc0135761
	v_mul_f32_e32 v66, 0xbdd2d3e7, v62
	v_fmaak_f32 v66, v62, v66, 0xc0135761
	v_mul_f32_e32 v66, v62, v66
	v_exp_f32_e32 v70, v66
	v_or_b32_e32 v66, 8, v1
	v_mul_f32_e32 v71, v63, v71
	v_add_f32_e32 v1, 1.0, v70
	v_mul_f32_e32 v70, 0xbdd2d3e7, v58
	v_fmaak_f32 v70, v58, v70, 0xc0135761
	v_mul_f32_e32 v70, v58, v70
	v_exp_f32_e32 v70, v70
	v_exp_f32_e32 v71, v71
	v_mul_f32_e32 v72, 0xbdd2d3e7, v59
	v_fmaak_f32 v72, v59, v72, 0xc0135761
	v_add_f32_e32 v70, 1.0, v70
	v_add_f32_e32 v71, 1.0, v71
	v_rcp_f32_e32 v70, v70
	v_rcp_f32_e32 v71, v71
	v_mul_f32_e32 v72, v59, v72
	v_mul_f32_e32 v70, v58, v70
	v_mul_f32_e32 v58, v63, v71
	v_mul_f32_e32 v63, 0xbdd2d3e7, v64
	v_rcp_f32_e32 v1, v1
	v_exp_f32_e32 v72, v72
	v_fmaak_f32 v63, v64, v63, 0xc0135761
	v_mul_f32_e32 v63, v64, v63
	v_mul_f32_e32 v71, 0xbdd2d3e7, v60
	v_mul_f32_e32 v1, v62, v1
	v_add_f32_e32 v62, 1.0, v72
	v_fmaak_f32 v71, v60, v71, 0xc0135761
	v_rcp_f32_e32 v62, v62
	v_exp_f32_e32 v63, v63
	v_mul_f32_e32 v71, v60, v71
	v_exp_f32_e32 v71, v71
	v_mul_f32_e32 v72, v59, v62
	v_add_f32_e32 v59, 1.0, v63
	v_mul_f32_e32 v63, 0xbdd2d3e7, v65
	v_fmaak_f32 v63, v65, v63, 0xc0135761
	v_mul_f32_e32 v63, v65, v63
	v_add_f32_e32 v62, 1.0, v71
	v_mul_f32_e32 v71, 0xbdd2d3e7, v61
	v_fmaak_f32 v71, v61, v71, 0xc0135761
	v_exp_f32_e32 v63, v63
	v_mul_f32_e32 v71, v61, v71
; __device__ __forceinline__ unsigned cvt_pk_bf16(float lo, float hi) { unsigned r; asm volatile("v_cvt_pk_bf16_f32 %0, %1, %2" : "=v"(r) : "v"(lo), "v"(hi)); return r; }
; __device__ __forceinline__ float fexp2(float x) { return __builtin_amdgcn_exp2f(x); }
; __device__ __forceinline__ float frcp(float x) { return __builtin_amdgcn_rcpf(x); }
; __device__ __forceinline__ float gelu_t(float v) { const float u = 0.7978845608028654f * (v + 0.044715f * v * v * v); return v * sigm(2.f * u); }
; __device__ __forceinline__ float sigm(float v) { return frcp(1.f + fexp2(-LOG2E * v)); }
; __device__ __forceinline__ float silu(float v) { return v * sigm(v); }
;     __device__ __forceinline__ void operator()(const f32x4 (&acc)[2][2][4][2], const Unit& u, int wr, int wc, int fr, int fq) const {
;     ...
;         for (int bj = 0; bj < 2; ++bj) {
;             const int n = u.pn * 256 + bj * 128 + c8, i = n >> 4, c0 = n & 15;
; #pragma unroll
;             for (int ai = 0; ai < 2; ++ai)
; #pragma unroll
;                 for (int m = 0; m < 4; ++m) {
;                     const int row = row0 + ai * 128 + m * 16, b = row >> 6, chunk = row & 63; const size_t tok = (size_t)b * SEQ + chunk * LCH + i;
;                     f32x4 v0 = acc[ai][bj][m][0], v1 = acc[ai][bj][m][1];
; #pragma unroll
;                     for (int j = 0; j < 4; ++j) { v0[j] = gelu_t(v0[j]); v1[j] = gelu_t(v1[j]); }
;                     v4u w; w.x = pg8::cvt_pk_bf16(v0[0], v0[1]); w.y = pg8::cvt_pk_bf16(v0[2], v0[3]); w.z = pg8::cvt_pk_bf16(v1[0], v1[1]); w.w = pg8::cvt_pk_bf16(v1[2], v1[3]);
;                     *(v4u*)(YG + tok * 512 + u.pz * 16 + c0) = w;
;                 }
;         }
	v_exp_f32_e32 v71, v71
	v_add_f32_e32 v63, 1.0, v63
	v_rcp_f32_e32 v59, v59
	v_rcp_f32_e32 v62, v62
	v_rcp_f32_e32 v63, v63
	v_mov_b32_e32 v67, v137
	v_lshl_add_u64 v[68:69], s[4:5], 0, v[66:67]
	v_add_f32_e32 v71, 1.0, v71
	v_rcp_f32_e32 v71, v71
	v_mul_f32_e32 v59, v64, v59
	v_mul_f32_e32 v64, v60, v62
	v_mul_f32_e32 v60, v65, v63
	v_lshl_add_u64 v[62:63], v[68:69], 0, v[136:137]
	v_lshlrev_b64 v[62:63], 10, v[62:63]
	v_lshl_add_u64 v[62:63], s[0:1], 0, v[62:63]
	v_lshl_add_u64 v[62:63], v[62:63], 0, s[2:3]
	v_mul_f32_e32 v61, v61, v71
	v_cvt_pk_bf16_f32 v58, v1, v58
	v_cvt_pk_bf16_f32 v59, v59, v60
	v_lshl_add_u64 v[62:63], v[62:63], 0, v[122:123]
	v_cvt_pk_bf16_f32 v60, v70, v72
	v_cvt_pk_bf16_f32 v61, v64, v61
	global_store_dwordx4 v[62:63], v[58:61], off
	v_mul_f32_e32 v1, 0xbdd2d3e7, v54
	v_fmaak_f32 v1, v54, v1, 0xc0135761
	v_mul_f32_e32 v58, 0xbdd2d3e7, v50
	v_mul_f32_e32 v59, 0xbdd2d3e7, v55
	v_fmaak_f32 v58, v50, v58, 0xc0135761
	v_fmaak_f32 v59, v55, v59, 0xc0135761
	v_mul_f32_e32 v58, v50, v58
	v_mul_f32_e32 v59, v55, v59
	v_exp_f32_e32 v58, v58
	v_exp_f32_e32 v59, v59
	v_mul_f32_e32 v1, v54, v1
	v_add_f32_e32 v58, 1.0, v58
	v_add_f32_e32 v59, 1.0, v59
	v_mul_f32_e32 v60, 0xbdd2d3e7, v51
	v_exp_f32_e32 v1, v1
	v_rcp_f32_e32 v58, v58
	v_rcp_f32_e32 v59, v59
	v_fmaak_f32 v60, v51, v60, 0xc0135761
	v_mul_f32_e32 v60, v51, v60
	v_add_f32_e32 v1, 1.0, v1
	v_mul_f32_e32 v58, v50, v58
	v_mul_f32_e32 v50, v55, v59
	v_mul_f32_e32 v55, 0xbdd2d3e7, v56
	v_rcp_f32_e32 v1, v1
	v_exp_f32_e32 v60, v60
	v_fmaak_f32 v55, v56, v55, 0xc0135761
	v_mul_f32_e32 v55, v56, v55
	v_mul_f32_e32 v59, 0xbdd2d3e7, v52
	v_mul_f32_e32 v1, v54, v1
	v_add_f32_e32 v54, 1.0, v60
	v_fmaak_f32 v59, v52, v59, 0xc0135761
	v_rcp_f32_e32 v54, v54
	v_exp_f32_e32 v55, v55
	v_mul_f32_e32 v59, v52, v59
	v_exp_f32_e32 v59, v59
	v_mul_f32_e32 v60, v51, v54
	v_add_f32_e32 v51, 1.0, v55
	v_mul_f32_e32 v55, 0xbdd2d3e7, v57
	v_fmaak_f32 v55, v57, v55, 0xc0135761
	v_mul_f32_e32 v55, v57, v55
	v_add_f32_e32 v54, 1.0, v59
	v_mul_f32_e32 v59, 0xbdd2d3e7, v53
	v_fmaak_f32 v59, v53, v59, 0xc0135761
	v_exp_f32_e32 v55, v55
	v_mul_f32_e32 v59, v53, v59
	v_exp_f32_e32 v59, v59
	v_add_f32_e32 v55, 1.0, v55
	v_rcp_f32_e32 v51, v51
	v_rcp_f32_e32 v54, v54
	v_rcp_f32_e32 v55, v55
	v_add_f32_e32 v59, 1.0, v59
	v_rcp_f32_e32 v59, v59
	v_mul_f32_e32 v51, v56, v51
	v_mul_f32_e32 v56, v52, v54
	v_mul_f32_e32 v52, v57, v55
	v_lshl_add_u64 v[54:55], v[68:69], 0, v[134:135]
	v_lshlrev_b64 v[54:55], 10, v[54:55]
	v_lshl_add_u64 v[54:55], s[0:1], 0, v[54:55]
	v_lshl_add_u64 v[54:55], v[54:55], 0, s[2:3]
	v_mul_f32_e32 v53, v53, v59
	v_cvt_pk_bf16_f32 v50, v1, v50
	v_cvt_pk_bf16_f32 v51, v51, v52
	v_lshl_add_u64 v[54:55], v[54:55], 0, v[122:123]
	v_cvt_pk_bf16_f32 v52, v58, v60
	v_cvt_pk_bf16_f32 v53, v56, v53
	global_store_dwordx4 v[54:55], v[50:53], off
	v_mul_f32_e32 v1, 0xbdd2d3e7, v46
	v_fmaak_f32 v1, v46, v1, 0xc0135761
	v_mul_f32_e32 v50, 0xbdd2d3e7, v42
	v_mul_f32_e32 v51, 0xbdd2d3e7, v47
	v_fmaak_f32 v50, v42, v50, 0xc0135761
	v_fmaak_f32 v51, v47, v51, 0xc0135761
	v_mul_f32_e32 v50, v42, v50
	v_mul_f32_e32 v51, v47, v51
	v_exp_f32_e32 v50, v50
	v_exp_f32_e32 v51, v51
	v_mul_f32_e32 v1, v46, v1
	v_add_f32_e32 v50, 1.0, v50
	v_add_f32_e32 v51, 1.0, v51
	v_mul_f32_e32 v52, 0xbdd2d3e7, v43
	v_exp_f32_e32 v1, v1
	v_rcp_f32_e32 v50, v50
	v_rcp_f32_e32 v51, v51
	v_fmaak_f32 v52, v43, v52, 0xc0135761
	v_mul_f32_e32 v52, v43, v52
	v_add_f32_e32 v1, 1.0, v1
	v_mul_f32_e32 v50, v42, v50
	v_mul_f32_e32 v42, v47, v51
	v_mul_f32_e32 v47, 0xbdd2d3e7, v48
	v_rcp_f32_e32 v1, v1
	v_exp_f32_e32 v52, v52
	v_fmaak_f32 v47, v48, v47, 0xc0135761
	v_mul_f32_e32 v47, v48, v47
	v_mul_f32_e32 v51, 0xbdd2d3e7, v44
	v_mul_f32_e32 v1, v46, v1
	v_add_f32_e32 v46, 1.0, v52
	v_fmaak_f32 v51, v44, v51, 0xc0135761
	v_rcp_f32_e32 v46, v46
	v_exp_f32_e32 v47, v47
	v_mul_f32_e32 v51, v44, v51
	v_exp_f32_e32 v51, v51
	v_mul_f32_e32 v52, v43, v46
	v_add_f32_e32 v43, 1.0, v47
	v_mul_f32_e32 v47, 0xbdd2d3e7, v49
	v_fmaak_f32 v47, v49, v47, 0xc0135761
	v_mul_f32_e32 v47, v49, v47
	v_add_f32_e32 v46, 1.0, v51
	v_mul_f32_e32 v51, 0xbdd2d3e7, v45
	v_fmaak_f32 v51, v45, v51, 0xc0135761
	v_exp_f32_e32 v47, v47
	v_mul_f32_e32 v51, v45, v51
	v_exp_f32_e32 v51, v51
	v_add_f32_e32 v47, 1.0, v47
	v_rcp_f32_e32 v43, v43
	v_rcp_f32_e32 v46, v46
	v_rcp_f32_e32 v47, v47
	v_add_f32_e32 v51, 1.0, v51
	v_rcp_f32_e32 v51, v51
	v_mul_f32_e32 v43, v48, v43
	v_mul_f32_e32 v48, v44, v46
	v_mul_f32_e32 v44, v49, v47
	v_lshl_add_u64 v[46:47], v[68:69], 0, v[132:133]
	v_lshlrev_b64 v[46:47], 10, v[46:47]
	v_lshl_add_u64 v[46:47], s[0:1], 0, v[46:47]
	v_lshl_add_u64 v[46:47], v[46:47], 0, s[2:3]
	v_mul_f32_e32 v45, v45, v51
	v_cvt_pk_bf16_f32 v42, v1, v42
	v_cvt_pk_bf16_f32 v43, v43, v44
	v_lshl_add_u64 v[46:47], v[46:47], 0, v[122:123]
	v_cvt_pk_bf16_f32 v44, v50, v52
	v_cvt_pk_bf16_f32 v45, v48, v45
	global_store_dwordx4 v[46:47], v[42:45], off
	v_mul_f32_e32 v1, 0xbdd2d3e7, v38
	v_fmaak_f32 v1, v38, v1, 0xc0135761
	v_mul_f32_e32 v42, 0xbdd2d3e7, v34
	v_mul_f32_e32 v43, 0xbdd2d3e7, v39
	v_fmaak_f32 v42, v34, v42, 0xc0135761
	v_fmaak_f32 v43, v39, v43, 0xc0135761
	v_mul_f32_e32 v42, v34, v42
	v_mul_f32_e32 v43, v39, v43
	v_exp_f32_e32 v42, v42
	v_exp_f32_e32 v43, v43
	v_mul_f32_e32 v1, v38, v1
	v_add_f32_e32 v42, 1.0, v42
	v_add_f32_e32 v43, 1.0, v43
	v_mul_f32_e32 v44, 0xbdd2d3e7, v35
	v_exp_f32_e32 v1, v1
	v_rcp_f32_e32 v42, v42
	v_rcp_f32_e32 v43, v43
	v_fmaak_f32 v44, v35, v44, 0xc0135761
	v_mul_f32_e32 v44, v35, v44
	v_add_f32_e32 v1, 1.0, v1
	v_mul_f32_e32 v42, v34, v42
	v_mul_f32_e32 v34, v39, v43
	v_mul_f32_e32 v39, 0xbdd2d3e7, v40
	v_rcp_f32_e32 v1, v1
; __device__ __forceinline__ unsigned cvt_pk_bf16(float lo, float hi) { unsigned r; asm volatile("v_cvt_pk_bf16_f32 %0, %1, %2" : "=v"(r) : "v"(lo), "v"(hi)); return r; }
; __device__ __forceinline__ float fexp2(float x) { return __builtin_amdgcn_exp2f(x); }
; __device__ __forceinline__ float frcp(float x) { return __builtin_amdgcn_rcpf(x); }
; __device__ __forceinline__ float gelu_t(float v) { const float u = 0.7978845608028654f * (v + 0.044715f * v * v * v); return v * sigm(2.f * u); }
; __device__ __forceinline__ float sigm(float v) { return frcp(1.f + fexp2(-LOG2E * v)); }
; __device__ __forceinline__ float silu(float v) { return v * sigm(v); }
;     __device__ __forceinline__ void operator()(const f32x4 (&acc)[2][2][4][2], const Unit& u, int wr, int wc, int fr, int fq) const {
;     ...
;         for (int bj = 0; bj < 2; ++bj) {
;             const int n = u.pn * 256 + bj * 128 + c8, i = n >> 4, c0 = n & 15;
; #pragma unroll
;             for (int ai = 0; ai < 2; ++ai)
; #pragma unroll
;                 for (int m = 0; m < 4; ++m) {
;                     const int row = row0 + ai * 128 + m * 16, b = row >> 6, chunk = row & 63; const size_t tok = (size_t)b * SEQ + chunk * LCH + i;
;                     f32x4 v0 = acc[ai][bj][m][0], v1 = acc[ai][bj][m][1];
; #pragma unroll
;                     for (int j = 0; j < 4; ++j) { v0[j] = gelu_t(v0[j]); v1[j] = gelu_t(v1[j]); }
;                     v4u w; w.x = pg8::cvt_pk_bf16(v0[0], v0[1]); w.y = pg8::cvt_pk_bf16(v0[2], v0[3]); w.z = pg8::cvt_pk_bf16(v1[0], v1[1]); w.w = pg8::cvt_pk_bf16(v1[2], v1[3]);
;                     *(v4u*)(YG + tok * 512 + u.pz * 16 + c0) = w;
;                 }
;         }
	v_exp_f32_e32 v44, v44
	v_fmaak_f32 v39, v40, v39, 0xc0135761
	v_mul_f32_e32 v39, v40, v39
	v_mul_f32_e32 v43, 0xbdd2d3e7, v36
	v_fmaak_f32 v43, v36, v43, 0xc0135761
	v_mul_f32_e32 v1, v38, v1
	v_add_f32_e32 v38, 1.0, v44
	v_mul_f32_e32 v43, v36, v43
	v_rcp_f32_e32 v38, v38
	v_exp_f32_e32 v39, v39
	v_exp_f32_e32 v43, v43
	v_mul_f32_e32 v44, v35, v38
	v_add_f32_e32 v35, 1.0, v39
	v_mul_f32_e32 v39, 0xbdd2d3e7, v41
	v_fmaak_f32 v39, v41, v39, 0xc0135761
	v_mul_f32_e32 v39, v41, v39
	v_add_f32_e32 v38, 1.0, v43
	v_mul_f32_e32 v43, 0xbdd2d3e7, v37
	v_fmaak_f32 v43, v37, v43, 0xc0135761
	v_mul_f32_e32 v43, v37, v43
	v_exp_f32_e32 v39, v39
	v_exp_f32_e32 v43, v43
	v_add_f32_e32 v39, 1.0, v39
	v_rcp_f32_e32 v35, v35
	v_rcp_f32_e32 v38, v38
	v_rcp_f32_e32 v39, v39
	v_add_f32_e32 v43, 1.0, v43
	v_rcp_f32_e32 v43, v43
	v_mul_f32_e32 v35, v40, v35
	v_mul_f32_e32 v40, v36, v38
	v_mul_f32_e32 v36, v41, v39
	v_lshl_add_u64 v[38:39], v[68:69], 0, v[130:131]
	v_lshlrev_b64 v[38:39], 10, v[38:39]
	v_lshl_add_u64 v[38:39], s[0:1], 0, v[38:39]
	v_mul_f32_e32 v37, v37, v43
	v_lshl_add_u64 v[38:39], v[38:39], 0, s[2:3]
	v_cvt_pk_bf16_f32 v34, v1, v34
	v_cvt_pk_bf16_f32 v35, v35, v36
	v_cvt_pk_bf16_f32 v36, v42, v44
	v_cvt_pk_bf16_f32 v37, v40, v37
	v_lshl_add_u64 v[38:39], v[38:39], 0, v[122:123]
	global_store_dwordx4 v[38:39], v[34:37], off
	v_mul_f32_e32 v1, 0xbdd2d3e7, v30
	v_fmaak_f32 v1, v30, v1, 0xc0135761
	v_mul_f32_e32 v36, 0xbdd2d3e7, v26
	v_mul_f32_e32 v37, 0xbdd2d3e7, v31
	v_fmaak_f32 v36, v26, v36, 0xc0135761
	v_fmaak_f32 v37, v31, v37, 0xc0135761
	v_mul_f32_e32 v36, v26, v36
	v_mul_f32_e32 v37, v31, v37
	v_exp_f32_e32 v36, v36
	v_exp_f32_e32 v37, v37
	v_mul_f32_e32 v1, v30, v1
	v_add_f32_e32 v36, 1.0, v36
	v_add_f32_e32 v37, 1.0, v37
	v_mul_f32_e32 v38, 0xbdd2d3e7, v27
	v_exp_f32_e32 v1, v1
	v_rcp_f32_e32 v36, v36
	v_rcp_f32_e32 v37, v37
	v_fmaak_f32 v38, v27, v38, 0xc0135761
	v_mul_f32_e32 v38, v27, v38
	v_add_f32_e32 v1, 1.0, v1
	v_mul_f32_e32 v36, v26, v36
	v_mul_f32_e32 v26, v31, v37
	v_mul_f32_e32 v31, 0xbdd2d3e7, v32
	v_rcp_f32_e32 v1, v1
	v_exp_f32_e32 v38, v38
	v_fmaak_f32 v31, v32, v31, 0xc0135761
	v_mul_f32_e32 v31, v32, v31
	v_mul_f32_e32 v37, 0xbdd2d3e7, v28
	v_mul_f32_e32 v1, v30, v1
	v_add_f32_e32 v30, 1.0, v38
	v_fmaak_f32 v37, v28, v37, 0xc0135761
	v_rcp_f32_e32 v30, v30
	v_exp_f32_e32 v31, v31
	v_mul_f32_e32 v37, v28, v37
	v_exp_f32_e32 v37, v37
	v_mul_f32_e32 v38, v27, v30
	v_add_f32_e32 v27, 1.0, v31
	v_mul_f32_e32 v31, 0xbdd2d3e7, v33
	v_fmaak_f32 v31, v33, v31, 0xc0135761
	v_mul_f32_e32 v31, v33, v31
	v_add_f32_e32 v30, 1.0, v37
	v_mul_f32_e32 v37, 0xbdd2d3e7, v29
	v_fmaak_f32 v37, v29, v37, 0xc0135761
	v_exp_f32_e32 v31, v31
	v_mul_f32_e32 v37, v29, v37
	v_exp_f32_e32 v37, v37
	v_add_f32_e32 v31, 1.0, v31
	v_rcp_f32_e32 v27, v27
	v_rcp_f32_e32 v30, v30
	v_rcp_f32_e32 v31, v31
	v_lshl_add_u64 v[34:35], s[8:9], 0, v[66:67]
	v_add_f32_e32 v37, 1.0, v37
	v_rcp_f32_e32 v37, v37
	v_mul_f32_e32 v27, v32, v27
	v_mul_f32_e32 v32, v28, v30
	v_mul_f32_e32 v28, v33, v31
	v_lshl_add_u64 v[30:31], v[34:35], 0, v[136:137]
	v_lshlrev_b64 v[30:31], 10, v[30:31]
	v_lshl_add_u64 v[30:31], s[0:1], 0, v[30:31]
	v_lshl_add_u64 v[30:31], v[30:31], 0, s[2:3]
	v_mul_f32_e32 v29, v29, v37
	v_cvt_pk_bf16_f32 v26, v1, v26
	v_cvt_pk_bf16_f32 v27, v27, v28
	v_lshl_add_u64 v[30:31], v[30:31], 0, v[122:123]
	v_cvt_pk_bf16_f32 v28, v36, v38
	v_cvt_pk_bf16_f32 v29, v32, v29
	global_store_dwordx4 v[30:31], v[26:29], off
	v_mul_f32_e32 v1, 0xbdd2d3e7, v22
	v_fmaak_f32 v1, v22, v1, 0xc0135761
	v_mul_f32_e32 v26, 0xbdd2d3e7, v18
	v_mul_f32_e32 v27, 0xbdd2d3e7, v23
	v_fmaak_f32 v26, v18, v26, 0xc0135761
	v_fmaak_f32 v27, v23, v27, 0xc0135761
	v_mul_f32_e32 v26, v18, v26
	v_mul_f32_e32 v27, v23, v27
	v_exp_f32_e32 v26, v26
	v_exp_f32_e32 v27, v27
	v_mul_f32_e32 v1, v22, v1
	v_add_f32_e32 v26, 1.0, v26
	v_add_f32_e32 v27, 1.0, v27
	v_mul_f32_e32 v28, 0xbdd2d3e7, v19
	v_exp_f32_e32 v1, v1
	v_rcp_f32_e32 v26, v26
	v_rcp_f32_e32 v27, v27
	v_fmaak_f32 v28, v19, v28, 0xc0135761
	v_mul_f32_e32 v28, v19, v28
	v_add_f32_e32 v1, 1.0, v1
	v_mul_f32_e32 v26, v18, v26
	v_mul_f32_e32 v18, v23, v27
	v_mul_f32_e32 v23, 0xbdd2d3e7, v24
	v_rcp_f32_e32 v1, v1
	v_exp_f32_e32 v28, v28
	v_fmaak_f32 v23, v24, v23, 0xc0135761
	v_mul_f32_e32 v23, v24, v23
	v_mul_f32_e32 v27, 0xbdd2d3e7, v20
	v_mul_f32_e32 v1, v22, v1
	v_add_f32_e32 v22, 1.0, v28
	v_fmaak_f32 v27, v20, v27, 0xc0135761
	v_rcp_f32_e32 v22, v22
	v_exp_f32_e32 v23, v23
	v_mul_f32_e32 v27, v20, v27
	v_exp_f32_e32 v27, v27
	v_mul_f32_e32 v28, v19, v22
	v_add_f32_e32 v19, 1.0, v23
	v_mul_f32_e32 v23, 0xbdd2d3e7, v25
	v_fmaak_f32 v23, v25, v23, 0xc0135761
	v_mul_f32_e32 v23, v25, v23
	v_add_f32_e32 v22, 1.0, v27
	v_mul_f32_e32 v27, 0xbdd2d3e7, v21
	v_fmaak_f32 v27, v21, v27, 0xc0135761
	v_exp_f32_e32 v23, v23
	v_mul_f32_e32 v27, v21, v27
; __device__ __forceinline__ unsigned cvt_pk_bf16(float lo, float hi) { unsigned r; asm volatile("v_cvt_pk_bf16_f32 %0, %1, %2" : "=v"(r) : "v"(lo), "v"(hi)); return r; }
; #define PG8_WAIT_V(n) asm volatile("s_waitcnt vmcnt(" #n ")" ::: "memory")
; #define PG8_BAR __builtin_amdgcn_s_barrier()
; __device__ __forceinline__ float gelu_t(float v) { const float u = 0.7978845608028654f * (v + 0.044715f * v * v * v); return v * sigm(2.f * u); }
; template <class Epi, class Sched, bool ALIGN_EPI = false, bool SP2 = false, bool FP8 = false>
; __device__ __forceinline__ void gemm_phase(PG8_LAS unsigned char* lds, const Gemm g, const Sched& S, const Epi& E) {
;     ...
;     PG8_WAIT_V(0);
;     if constexpr (!ALIGN_EPI) { if (wr == 0) PG8_BAR; }
;     PG8_BAR;
;     __device__ __forceinline__ void operator()(const f32x4 (&acc)[2][2][4][2], const Unit& u, int wr, int wc, int fr, int fq) const {
;     ...
;         for (int bj = 0; bj < 2; ++bj) {
;             const int n = u.pn * 256 + bj * 128 + c8, i = n >> 4, c0 = n & 15;
; #pragma unroll
;             for (int ai = 0; ai < 2; ++ai)
; #pragma unroll
;                 for (int m = 0; m < 4; ++m) {
;                     const int row = row0 + ai * 128 + m * 16, b = row >> 6, chunk = row & 63; const size_t tok = (size_t)b * SEQ + chunk * LCH + i;
;                     f32x4 v0 = acc[ai][bj][m][0], v1 = acc[ai][bj][m][1];
; #pragma unroll
;                     for (int j = 0; j < 4; ++j) { v0[j] = gelu_t(v0[j]); v1[j] = gelu_t(v1[j]); }
;                     v4u w; w.x = pg8::cvt_pk_bf16(v0[0], v0[1]); w.y = pg8::cvt_pk_bf16(v0[2], v0[3]); w.z = pg8::cvt_pk_bf16(v1[0], v1[1]); w.w = pg8::cvt_pk_bf16(v1[2], v1[3]);
;                     *(v4u*)(YG + tok * 512 + u.pz * 16 + c0) = w;
;                 }
;         }
	v_exp_f32_e32 v27, v27
	v_add_f32_e32 v23, 1.0, v23
	v_rcp_f32_e32 v19, v19
	v_rcp_f32_e32 v22, v22
	v_rcp_f32_e32 v23, v23
	v_add_f32_e32 v27, 1.0, v27
	v_rcp_f32_e32 v27, v27
	v_mul_f32_e32 v19, v24, v19
	v_mul_f32_e32 v24, v20, v22
	v_mul_f32_e32 v20, v25, v23
	v_lshl_add_u64 v[22:23], v[34:35], 0, v[134:135]
	v_lshlrev_b64 v[22:23], 10, v[22:23]
	v_lshl_add_u64 v[22:23], s[0:1], 0, v[22:23]
	v_lshl_add_u64 v[22:23], v[22:23], 0, s[2:3]
	v_mul_f32_e32 v21, v21, v27
	v_cvt_pk_bf16_f32 v18, v1, v18
	v_cvt_pk_bf16_f32 v19, v19, v20
	v_lshl_add_u64 v[22:23], v[22:23], 0, v[122:123]
	v_cvt_pk_bf16_f32 v20, v26, v28
	v_cvt_pk_bf16_f32 v21, v24, v21
	global_store_dwordx4 v[22:23], v[18:21], off
	v_mul_f32_e32 v1, 0xbdd2d3e7, v14
	v_fmaak_f32 v1, v14, v1, 0xc0135761
	v_mul_f32_e32 v18, 0xbdd2d3e7, v10
	v_mul_f32_e32 v19, 0xbdd2d3e7, v15
	v_fmaak_f32 v18, v10, v18, 0xc0135761
	v_fmaak_f32 v19, v15, v19, 0xc0135761
	v_mul_f32_e32 v18, v10, v18
	v_mul_f32_e32 v19, v15, v19
	v_exp_f32_e32 v18, v18
	v_exp_f32_e32 v19, v19
	v_mul_f32_e32 v1, v14, v1
	v_add_f32_e32 v18, 1.0, v18
	v_add_f32_e32 v19, 1.0, v19
	v_mul_f32_e32 v20, 0xbdd2d3e7, v11
	v_exp_f32_e32 v1, v1
	v_rcp_f32_e32 v18, v18
	v_rcp_f32_e32 v19, v19
	v_fmaak_f32 v20, v11, v20, 0xc0135761
	v_mul_f32_e32 v20, v11, v20
	v_add_f32_e32 v1, 1.0, v1
	v_mul_f32_e32 v18, v10, v18
	v_mul_f32_e32 v10, v15, v19
	v_mul_f32_e32 v15, 0xbdd2d3e7, v16
	v_rcp_f32_e32 v1, v1
	v_exp_f32_e32 v20, v20
	v_fmaak_f32 v15, v16, v15, 0xc0135761
	v_mul_f32_e32 v15, v16, v15
	v_mul_f32_e32 v19, 0xbdd2d3e7, v12
	v_mul_f32_e32 v1, v14, v1
	v_add_f32_e32 v14, 1.0, v20
	v_fmaak_f32 v19, v12, v19, 0xc0135761
	v_rcp_f32_e32 v14, v14
	v_exp_f32_e32 v15, v15
	v_mul_f32_e32 v19, v12, v19
	v_exp_f32_e32 v19, v19
	v_mul_f32_e32 v20, v11, v14
	v_add_f32_e32 v11, 1.0, v15
	v_mul_f32_e32 v15, 0xbdd2d3e7, v17
	v_fmaak_f32 v15, v17, v15, 0xc0135761
	v_mul_f32_e32 v15, v17, v15
	v_add_f32_e32 v14, 1.0, v19
	v_mul_f32_e32 v19, 0xbdd2d3e7, v13
	v_fmaak_f32 v19, v13, v19, 0xc0135761
	v_exp_f32_e32 v15, v15
	v_mul_f32_e32 v19, v13, v19
	v_exp_f32_e32 v19, v19
	v_add_f32_e32 v15, 1.0, v15
	v_rcp_f32_e32 v11, v11
	v_rcp_f32_e32 v14, v14
	v_rcp_f32_e32 v15, v15
	v_add_f32_e32 v19, 1.0, v19
	v_rcp_f32_e32 v19, v19
	v_mul_f32_e32 v11, v16, v11
	v_mul_f32_e32 v16, v12, v14
	v_mul_f32_e32 v12, v17, v15
	v_lshl_add_u64 v[14:15], v[34:35], 0, v[132:133]
	v_lshlrev_b64 v[14:15], 10, v[14:15]
	v_lshl_add_u64 v[14:15], s[0:1], 0, v[14:15]
	v_lshl_add_u64 v[14:15], v[14:15], 0, s[2:3]
	v_mul_f32_e32 v13, v13, v19
	v_cvt_pk_bf16_f32 v10, v1, v10
	v_cvt_pk_bf16_f32 v11, v11, v12
	v_lshl_add_u64 v[14:15], v[14:15], 0, v[122:123]
	v_cvt_pk_bf16_f32 v12, v18, v20
	v_cvt_pk_bf16_f32 v13, v16, v13
	global_store_dwordx4 v[14:15], v[10:13], off
	v_mul_f32_e32 v1, 0xbdd2d3e7, v6
	v_fmaak_f32 v1, v6, v1, 0xc0135761
	v_mul_f32_e32 v10, 0xbdd2d3e7, v2
	v_mul_f32_e32 v11, 0xbdd2d3e7, v7
	v_fmaak_f32 v10, v2, v10, 0xc0135761
	v_fmaak_f32 v11, v7, v11, 0xc0135761
	v_mul_f32_e32 v10, v2, v10
	v_mul_f32_e32 v11, v7, v11
	v_exp_f32_e32 v10, v10
	v_exp_f32_e32 v11, v11
	v_mul_f32_e32 v1, v6, v1
	v_add_f32_e32 v10, 1.0, v10
	v_add_f32_e32 v11, 1.0, v11
	v_mul_f32_e32 v12, 0xbdd2d3e7, v3
	v_exp_f32_e32 v1, v1
	v_rcp_f32_e32 v10, v10
	v_rcp_f32_e32 v11, v11
	v_fmaak_f32 v12, v3, v12, 0xc0135761
	v_mul_f32_e32 v12, v3, v12
	v_add_f32_e32 v1, 1.0, v1
	v_mul_f32_e32 v10, v2, v10
	v_mul_f32_e32 v2, v7, v11
	v_mul_f32_e32 v7, 0xbdd2d3e7, v8
	v_rcp_f32_e32 v1, v1
	v_exp_f32_e32 v12, v12
	v_fmaak_f32 v7, v8, v7, 0xc0135761
	v_mul_f32_e32 v7, v8, v7
	v_mul_f32_e32 v11, 0xbdd2d3e7, v4
	v_mul_f32_e32 v1, v6, v1
	v_add_f32_e32 v6, 1.0, v12
	v_fmaak_f32 v11, v4, v11, 0xc0135761
	v_rcp_f32_e32 v6, v6
	v_exp_f32_e32 v7, v7
	v_mul_f32_e32 v11, v4, v11
	v_exp_f32_e32 v11, v11
	v_mul_f32_e32 v12, v3, v6
	v_add_f32_e32 v3, 1.0, v7
	v_mul_f32_e32 v7, 0xbdd2d3e7, v9
	v_fmaak_f32 v7, v9, v7, 0xc0135761
	v_mul_f32_e32 v7, v9, v7
	v_add_f32_e32 v6, 1.0, v11
	v_mul_f32_e32 v11, 0xbdd2d3e7, v5
	v_fmaak_f32 v11, v5, v11, 0xc0135761
	v_exp_f32_e32 v7, v7
	v_mul_f32_e32 v11, v5, v11
	v_exp_f32_e32 v11, v11
	v_add_f32_e32 v7, 1.0, v7
	v_rcp_f32_e32 v3, v3
	v_rcp_f32_e32 v6, v6
	v_rcp_f32_e32 v7, v7
	v_add_f32_e32 v11, 1.0, v11
	v_rcp_f32_e32 v11, v11
	v_mul_f32_e32 v3, v8, v3
	v_mul_f32_e32 v8, v4, v6
	v_mul_f32_e32 v4, v9, v7
	v_lshl_add_u64 v[6:7], v[34:35], 0, v[130:131]
	v_lshlrev_b64 v[6:7], 10, v[6:7]
	v_lshl_add_u64 v[6:7], s[0:1], 0, v[6:7]
	v_lshl_add_u64 v[6:7], v[6:7], 0, s[2:3]
	v_mul_f32_e32 v5, v5, v11
	v_lshl_add_u64 v[6:7], v[6:7], 0, v[122:123]
	v_cvt_pk_bf16_f32 v2, v1, v2
	v_cvt_pk_bf16_f32 v3, v3, v4
	v_cvt_pk_bf16_f32 v4, v10, v12
	v_cvt_pk_bf16_f32 v5, v8, v5
	global_store_dwordx4 v[6:7], v[2:5], off
	s_waitcnt vmcnt(0)
	s_cmpk_lt_u32 s22, 0x100
	s_cbranch_scc0 .LBB0_504
	s_barrier

; __device__ __forceinline__ unsigned cvt_pk_bf16(float lo, float hi) { unsigned r; asm volatile("v_cvt_pk_bf16_f32 %0, %1, %2" : "=v"(r) : "v"(lo), "v"(hi)); return r; }
; __device__ __forceinline__ float bflo(unsigned w) { return __uint_as_float(w << 16); }
; __device__ __forceinline__ float bfhi(unsigned w) { return __uint_as_float(w & 0xffff0000u); }
; __device__ __forceinline__ float sigm(float v) { return frcp(1.f + fexp2(-LOG2E * v)); }
;     __device__ __forceinline__ void operator()(const f32x4 (&acc)[2][2][4][2], const Unit& u, int wr, int wc, int fr, int fq) const { if (u.pn >= 9) g(acc, u, wr, wc, fr, fq); else a(acc, u, wr, wc, fr, fq); }
;     __device__ __forceinline__ void operator()(const f32x4 (&acc)[2][2][4][2], const Unit& u, int wr, int wc, int fr, int fq) const {
;         const int row0 = u.pm * 256 + wr * 64 + fr, c8 = wc * 32 + 8 * fq;
; #pragma unroll
;         for (int bj = 0; bj < 2; ++bj) {
;             const int col = u.pn * 256 + bj * 128 + c8;
;             const f32x4 b0 = *(const f32x4*)(b_glu + col), b1 = *(const f32x4*)(b_glu + col + 4);
; #pragma unroll
;             for (int ai = 0; ai < 2; ++ai)
; #pragma unroll
;                 for (int m = 0; m < 4; ++m) {
;                     const size_t row = (size_t)(row0 + ai * 128 + m * 16);
;                     const v4u y = __builtin_nontemporal_load((const v4u*)(YG + row * 512 + col)), z = __builtin_nontemporal_load((const v4u*)(ZS + row * 512 + col));
;                     const f32x4 a0 = acc[ai][bj][m][0], a1 = acc[ai][bj][m][1];
;                     v4u w;
;                     w.x = pg8::cvt_pk_bf16(bflo(y.x) * sigm(a0[0] + b0[0]) * bflo(z.x), bfhi(y.x) * sigm(a0[1] + b0[1]) * bfhi(z.x));
;                     w.y = pg8::cvt_pk_bf16(bflo(y.y) * sigm(a0[2] + b0[2]) * bflo(z.y), bfhi(y.y) * sigm(a0[3] + b0[3]) * bfhi(z.y));
;                     w.z = pg8::cvt_pk_bf16(bflo(y.z) * sigm(a1[0] + b1[0]) * bflo(z.z), bfhi(y.z) * sigm(a1[1] + b1[1]) * bfhi(z.z));
;                     w.w = pg8::cvt_pk_bf16(bflo(y.w) * sigm(a1[2] + b1[2]) * bflo(z.w), bfhi(y.w) * sigm(a1[3] + b1[3]) * bfhi(z.w));
;                     *(v4u*)(A5 + row * 1024 + 512 + col) = w;
;                 }
;         }
.LBB0_667:
	v_lshl_or_b32 v152, s33, 8, v165
	v_ashrrev_i32_e32 v153, 31, v152
	v_lshl_add_u64 v[154:155], v[152:153], 2, s[50:51]
	global_load_dwordx4 v[110:113], v[154:155], off
	global_load_dwordx4 v[106:109], v[154:155], off offset:16
	global_load_dwordx4 v[170:173], v[154:155], off offset:512
	global_load_dwordx4 v[174:177], v[154:155], off offset:528
	v_lshl_add_u32 v162, s36, 8, v1
	v_ashrrev_i32_e32 v163, 31, v162
	v_lshlrev_b64 v[156:157], 1, v[152:153]
	v_lshlrev_b64 v[158:159], 10, v[162:163]
	v_lshl_add_u64 v[158:159], v[158:159], 0, v[156:157]
	v_lshlrev_b64 v[160:161], 11, v[162:163]
	v_lshl_add_u64 v[160:161], v[160:161], 0, v[156:157]
	v_lshl_add_u64 v[160:161], s[8:9], 0, v[160:161]
	v_lshl_add_u64 v[152:153], s[0:1], 0, v[158:159]
	v_lshl_add_u64 v[154:155], s[6:7], 0, v[158:159]
	v_mov_b32_e32 v162, v152
	v_mov_b32_e32 v163, v153
	v_mov_b32_e32 v184, v154
	v_mov_b32_e32 v185, v155
	v_mov_b32_e32 v182, v160
	v_mov_b32_e32 v183, v161
	v_mov_b32_e32 v156, 0x4000
	v_mov_b32_e32 v157, 0
	v_mov_b32_e32 v158, 0x14000
	v_mov_b32_e32 v159, 0
	v_mov_b32_e32 v178, 0x8000
	v_mov_b32_e32 v179, 0
	v_mov_b32_e32 v180, 0x28000
	v_mov_b32_e32 v181, 0
	s_andn2_b64 vcc, exec, s[26:27]
	s_mov_b64 s[26:27], -1
	global_load_dwordx4 v[186:189], v[152:153], off nt
	global_load_dwordx4 v[190:193], v[154:155], off nt
	v_lshl_add_u64 v[152:153], v[152:153], 0, v[156:157]
	v_lshl_add_u64 v[154:155], v[154:155], 0, v[156:157]
	global_load_dwordx4 v[194:197], v[152:153], off nt
	global_load_dwordx4 v[198:201], v[154:155], off nt
	v_lshl_add_u64 v[152:153], v[152:153], 0, v[156:157]
	v_lshl_add_u64 v[154:155], v[154:155], 0, v[156:157]
	global_load_dwordx4 v[202:205], v[152:153], off nt
	global_load_dwordx4 v[206:209], v[154:155], off nt
	v_lshl_add_u64 v[152:153], v[152:153], 0, v[156:157]
	v_lshl_add_u64 v[154:155], v[154:155], 0, v[156:157]
	global_load_dwordx4 v[210:213], v[152:153], off nt
	global_load_dwordx4 v[214:217], v[154:155], off nt
	v_lshl_add_u64 v[152:153], v[152:153], 0, v[158:159]
	v_lshl_add_u64 v[154:155], v[154:155], 0, v[158:159]
	global_load_dwordx4 v[218:221], v[152:153], off nt
	global_load_dwordx4 v[222:225], v[154:155], off nt
	v_lshl_add_u64 v[152:153], v[152:153], 0, v[156:157]
	v_lshl_add_u64 v[154:155], v[154:155], 0, v[156:157]
	global_load_dwordx4 v[226:229], v[152:153], off nt
	global_load_dwordx4 v[230:233], v[154:155], off nt
	v_lshl_add_u64 v[152:153], v[152:153], 0, v[156:157]
	v_lshl_add_u64 v[154:155], v[154:155], 0, v[156:157]
	global_load_dwordx4 v[234:237], v[152:153], off nt
	global_load_dwordx4 v[238:241], v[154:155], off nt
	v_lshl_add_u64 v[152:153], v[152:153], 0, v[156:157]
	v_lshl_add_u64 v[154:155], v[154:155], 0, v[156:157]
	global_load_dwordx4 v[242:245], v[152:153], off nt
	global_load_dwordx4 v[246:249], v[154:155], off nt
	s_waitcnt vmcnt(16)
	v_mul_f32_e32 v110, 0xbfb8aa3b, v110
	v_mul_f32_e32 v111, 0xbfb8aa3b, v111
	v_mul_f32_e32 v112, 0xbfb8aa3b, v112
	v_mul_f32_e32 v113, 0xbfb8aa3b, v113
	v_mul_f32_e32 v106, 0xbfb8aa3b, v106
	v_mul_f32_e32 v107, 0xbfb8aa3b, v107
	v_mul_f32_e32 v108, 0xbfb8aa3b, v108
	v_mul_f32_e32 v109, 0xbfb8aa3b, v109
	v_mul_f32_e32 v170, 0xbfb8aa3b, v170
	v_mul_f32_e32 v171, 0xbfb8aa3b, v171
	v_mul_f32_e32 v172, 0xbfb8aa3b, v172
	v_mul_f32_e32 v173, 0xbfb8aa3b, v173
	v_mul_f32_e32 v174, 0xbfb8aa3b, v174
	v_mul_f32_e32 v175, 0xbfb8aa3b, v175
	v_mul_f32_e32 v176, 0xbfb8aa3b, v176
	v_mul_f32_e32 v177, 0xbfb8aa3b, v177
	v_fmamk_f32 v134, v134, 0xbfb8aa3b, v110
	v_fmamk_f32 v135, v135, 0xbfb8aa3b, v111
	v_fmamk_f32 v136, v136, 0xbfb8aa3b, v112
	v_fmamk_f32 v137, v137, 0xbfb8aa3b, v113
	v_fmamk_f32 v130, v130, 0xbfb8aa3b, v106
	v_fmamk_f32 v131, v131, 0xbfb8aa3b, v107
	v_fmamk_f32 v132, v132, 0xbfb8aa3b, v108
	v_fmamk_f32 v133, v133, 0xbfb8aa3b, v109
	v_exp_f32_e32 v134, v134
	v_exp_f32_e32 v135, v135
	v_exp_f32_e32 v136, v136
	v_exp_f32_e32 v137, v137
	v_exp_f32_e32 v130, v130
	v_exp_f32_e32 v131, v131
	v_exp_f32_e32 v132, v132
	v_exp_f32_e32 v133, v133
	v_add_f32_e32 v134, 1.0, v134
	v_add_f32_e32 v135, 1.0, v135
	v_add_f32_e32 v136, 1.0, v136
	v_add_f32_e32 v137, 1.0, v137
	v_add_f32_e32 v130, 1.0, v130
	v_add_f32_e32 v131, 1.0, v131
	v_add_f32_e32 v132, 1.0, v132
	v_add_f32_e32 v133, 1.0, v133
	v_rcp_f32_e32 v134, v134
	v_rcp_f32_e32 v135, v135
	v_rcp_f32_e32 v136, v136
	v_rcp_f32_e32 v137, v137
	v_rcp_f32_e32 v130, v130
	v_rcp_f32_e32 v131, v131
	v_rcp_f32_e32 v132, v132
	v_rcp_f32_e32 v133, v133
	s_waitcnt vmcnt(14)
; __device__ __forceinline__ unsigned cvt_pk_bf16(float lo, float hi) { unsigned r; asm volatile("v_cvt_pk_bf16_f32 %0, %1, %2" : "=v"(r) : "v"(lo), "v"(hi)); return r; }
; __device__ __forceinline__ float bflo(unsigned w) { return __uint_as_float(w << 16); }
; __device__ __forceinline__ float bfhi(unsigned w) { return __uint_as_float(w & 0xffff0000u); }
; __device__ __forceinline__ float sigm(float v) { return frcp(1.f + fexp2(-LOG2E * v)); }
;     __device__ __forceinline__ void operator()(const f32x4 (&acc)[2][2][4][2], const Unit& u, int wr, int wc, int fr, int fq) const {
;     ...
;         for (int bj = 0; bj < 2; ++bj) {
;             const int col = u.pn * 256 + bj * 128 + c8;
;             const f32x4 b0 = *(const f32x4*)(b_glu + col), b1 = *(const f32x4*)(b_glu + col + 4);
; #pragma unroll
;             for (int ai = 0; ai < 2; ++ai)
; #pragma unroll
;                 for (int m = 0; m < 4; ++m) {
;                     const size_t row = (size_t)(row0 + ai * 128 + m * 16);
;                     const v4u y = __builtin_nontemporal_load((const v4u*)(YG + row * 512 + col)), z = __builtin_nontemporal_load((const v4u*)(ZS + row * 512 + col));
;                     const f32x4 a0 = acc[ai][bj][m][0], a1 = acc[ai][bj][m][1];
;                     v4u w;
;                     w.x = pg8::cvt_pk_bf16(bflo(y.x) * sigm(a0[0] + b0[0]) * bflo(z.x), bfhi(y.x) * sigm(a0[1] + b0[1]) * bfhi(z.x));
;                     w.y = pg8::cvt_pk_bf16(bflo(y.y) * sigm(a0[2] + b0[2]) * bflo(z.y), bfhi(y.y) * sigm(a0[3] + b0[3]) * bfhi(z.y));
;                     w.z = pg8::cvt_pk_bf16(bflo(y.z) * sigm(a1[0] + b1[0]) * bflo(z.z), bfhi(y.z) * sigm(a1[1] + b1[1]) * bfhi(z.z));
;                     w.w = pg8::cvt_pk_bf16(bflo(y.w) * sigm(a1[2] + b1[2]) * bflo(z.w), bfhi(y.w) * sigm(a1[3] + b1[3]) * bfhi(z.w));
;                     *(v4u*)(A5 + row * 1024 + 512 + col) = w;
;                 }
;         }
	v_lshlrev_b32_e32 v146, 16, v186
	v_and_b32_e32 v147, 0xffff0000, v186
	v_lshlrev_b32_e32 v148, 16, v187
	v_and_b32_e32 v149, 0xffff0000, v187
	v_lshlrev_b32_e32 v150, 16, v188
	v_and_b32_e32 v151, 0xffff0000, v188
	v_lshlrev_b32_e32 v166, 16, v189
	v_and_b32_e32 v167, 0xffff0000, v189
	v_mul_f32_e32 v134, v134, v146
	v_mul_f32_e32 v135, v135, v147
	v_mul_f32_e32 v136, v136, v148
	v_mul_f32_e32 v137, v137, v149
	v_mul_f32_e32 v130, v130, v150
	v_mul_f32_e32 v131, v131, v151
	v_mul_f32_e32 v132, v132, v166
	v_mul_f32_e32 v133, v133, v167
	v_lshlrev_b32_e32 v146, 16, v190
	v_and_b32_e32 v147, 0xffff0000, v190
	v_lshlrev_b32_e32 v148, 16, v191
	v_and_b32_e32 v149, 0xffff0000, v191
	v_lshlrev_b32_e32 v150, 16, v192
	v_and_b32_e32 v151, 0xffff0000, v192
	v_lshlrev_b32_e32 v166, 16, v193
	v_and_b32_e32 v167, 0xffff0000, v193
	v_mul_f32_e32 v134, v134, v146
	v_mul_f32_e32 v135, v135, v147
	v_mul_f32_e32 v136, v136, v148
	v_mul_f32_e32 v137, v137, v149
	v_mul_f32_e32 v130, v130, v150
	v_mul_f32_e32 v131, v131, v151
	v_mul_f32_e32 v132, v132, v166
	v_mul_f32_e32 v133, v133, v167
	v_cvt_pk_bf16_f32 v138, v134, v135
	v_cvt_pk_bf16_f32 v139, v136, v137
	v_cvt_pk_bf16_f32 v140, v130, v131
	v_cvt_pk_bf16_f32 v141, v132, v133
	global_store_dwordx4 v[160:161], v[138:141], off offset:1024
	v_lshl_add_u64 v[160:161], v[160:161], 0, v[178:179]
	global_load_dwordx4 v[186:189], v[162:163], off offset:256 nt
	global_load_dwordx4 v[190:193], v[184:185], off offset:256 nt
	v_lshl_add_u64 v[162:163], v[162:163], 0, v[156:157]
	v_lshl_add_u64 v[184:185], v[184:185], 0, v[156:157]
	v_fmamk_f32 v126, v126, 0xbfb8aa3b, v110
	v_fmamk_f32 v127, v127, 0xbfb8aa3b, v111
	v_fmamk_f32 v128, v128, 0xbfb8aa3b, v112
	v_fmamk_f32 v129, v129, 0xbfb8aa3b, v113
	v_fmamk_f32 v122, v122, 0xbfb8aa3b, v106
	v_fmamk_f32 v123, v123, 0xbfb8aa3b, v107
	v_fmamk_f32 v124, v124, 0xbfb8aa3b, v108
	v_fmamk_f32 v125, v125, 0xbfb8aa3b, v109
	v_exp_f32_e32 v126, v126
	v_exp_f32_e32 v127, v127
	v_exp_f32_e32 v128, v128
	v_exp_f32_e32 v129, v129
	v_exp_f32_e32 v122, v122
	v_exp_f32_e32 v123, v123
	v_exp_f32_e32 v124, v124
	v_exp_f32_e32 v125, v125
	v_add_f32_e32 v126, 1.0, v126
	v_add_f32_e32 v127, 1.0, v127
	v_add_f32_e32 v128, 1.0, v128
	v_add_f32_e32 v129, 1.0, v129
	v_add_f32_e32 v122, 1.0, v122
	v_add_f32_e32 v123, 1.0, v123
	v_add_f32_e32 v124, 1.0, v124
	v_add_f32_e32 v125, 1.0, v125
	v_rcp_f32_e32 v126, v126
	v_rcp_f32_e32 v127, v127
	v_rcp_f32_e32 v128, v128
	v_rcp_f32_e32 v129, v129
	v_rcp_f32_e32 v122, v122
	v_rcp_f32_e32 v123, v123
	v_rcp_f32_e32 v124, v124
	v_rcp_f32_e32 v125, v125
	s_waitcnt vmcnt(15)
	v_lshlrev_b32_e32 v146, 16, v194
	v_and_b32_e32 v147, 0xffff0000, v194
	v_lshlrev_b32_e32 v148, 16, v195
	v_and_b32_e32 v149, 0xffff0000, v195
	v_lshlrev_b32_e32 v150, 16, v196
	v_and_b32_e32 v151, 0xffff0000, v196
	v_lshlrev_b32_e32 v166, 16, v197
	v_and_b32_e32 v167, 0xffff0000, v197
	v_mul_f32_e32 v126, v126, v146
	v_mul_f32_e32 v127, v127, v147
	v_mul_f32_e32 v128, v128, v148
	v_mul_f32_e32 v129, v129, v149
	v_mul_f32_e32 v122, v122, v150
	v_mul_f32_e32 v123, v123, v151
	v_mul_f32_e32 v124, v124, v166
	v_mul_f32_e32 v125, v125, v167
	v_lshlrev_b32_e32 v146, 16, v198
	v_and_b32_e32 v147, 0xffff0000, v198
	v_lshlrev_b32_e32 v148, 16, v199
	v_and_b32_e32 v149, 0xffff0000, v199
	v_lshlrev_b32_e32 v150, 16, v200
	v_and_b32_e32 v151, 0xffff0000, v200
	v_lshlrev_b32_e32 v166, 16, v201
	v_and_b32_e32 v167, 0xffff0000, v201
	v_mul_f32_e32 v126, v126, v146
	v_mul_f32_e32 v127, v127, v147
	v_mul_f32_e32 v128, v128, v148
	v_mul_f32_e32 v129, v129, v149
	v_mul_f32_e32 v122, v122, v150
	v_mul_f32_e32 v123, v123, v151
	v_mul_f32_e32 v124, v124, v166
	v_mul_f32_e32 v125, v125, v167
	v_cvt_pk_bf16_f32 v142, v126, v127
	v_cvt_pk_bf16_f32 v143, v128, v129
	v_cvt_pk_bf16_f32 v144, v122, v123
	v_cvt_pk_bf16_f32 v145, v124, v125
	global_store_dwordx4 v[160:161], v[142:145], off offset:1024
	v_lshl_add_u64 v[160:161], v[160:161], 0, v[178:179]
	global_load_dwordx4 v[194:197], v[162:163], off offset:256 nt
	global_load_dwordx4 v[198:201], v[184:185], off offset:256 nt
	v_lshl_add_u64 v[162:163], v[162:163], 0, v[156:157]
	v_lshl_add_u64 v[184:185], v[184:185], 0, v[156:157]
	v_fmamk_f32 v118, v118, 0xbfb8aa3b, v110
	v_fmamk_f32 v119, v119, 0xbfb8aa3b, v111
	v_fmamk_f32 v120, v120, 0xbfb8aa3b, v112
	v_fmamk_f32 v121, v121, 0xbfb8aa3b, v113
	v_fmamk_f32 v114, v114, 0xbfb8aa3b, v106
	v_fmamk_f32 v115, v115, 0xbfb8aa3b, v107
	v_fmamk_f32 v116, v116, 0xbfb8aa3b, v108
	v_fmamk_f32 v117, v117, 0xbfb8aa3b, v109
	v_exp_f32_e32 v118, v118
	v_exp_f32_e32 v119, v119
	v_exp_f32_e32 v120, v120
	v_exp_f32_e32 v121, v121
	v_exp_f32_e32 v114, v114
	v_exp_f32_e32 v115, v115
	v_exp_f32_e32 v116, v116
	v_exp_f32_e32 v117, v117
	v_add_f32_e32 v118, 1.0, v118
	v_add_f32_e32 v119, 1.0, v119
	v_add_f32_e32 v120, 1.0, v120
	v_add_f32_e32 v121, 1.0, v121
	v_add_f32_e32 v114, 1.0, v114
	v_add_f32_e32 v115, 1.0, v115
	v_add_f32_e32 v116, 1.0, v116
	v_add_f32_e32 v117, 1.0, v117
	v_rcp_f32_e32 v118, v118
	v_rcp_f32_e32 v119, v119
	v_rcp_f32_e32 v120, v120
	v_rcp_f32_e32 v121, v121
	v_rcp_f32_e32 v114, v114
	v_rcp_f32_e32 v115, v115
	v_rcp_f32_e32 v116, v116
	v_rcp_f32_e32 v117, v117
	s_waitcnt vmcnt(16)
; __device__ __forceinline__ unsigned cvt_pk_bf16(float lo, float hi) { unsigned r; asm volatile("v_cvt_pk_bf16_f32 %0, %1, %2" : "=v"(r) : "v"(lo), "v"(hi)); return r; }
; __device__ __forceinline__ float bflo(unsigned w) { return __uint_as_float(w << 16); }
; __device__ __forceinline__ float bfhi(unsigned w) { return __uint_as_float(w & 0xffff0000u); }
; __device__ __forceinline__ float sigm(float v) { return frcp(1.f + fexp2(-LOG2E * v)); }
;     __device__ __forceinline__ void operator()(const f32x4 (&acc)[2][2][4][2], const Unit& u, int wr, int wc, int fr, int fq) const {
;     ...
;         for (int bj = 0; bj < 2; ++bj) {
;             const int col = u.pn * 256 + bj * 128 + c8;
;             const f32x4 b0 = *(const f32x4*)(b_glu + col), b1 = *(const f32x4*)(b_glu + col + 4);
; #pragma unroll
;             for (int ai = 0; ai < 2; ++ai)
; #pragma unroll
;                 for (int m = 0; m < 4; ++m) {
;                     const size_t row = (size_t)(row0 + ai * 128 + m * 16);
;                     const v4u y = __builtin_nontemporal_load((const v4u*)(YG + row * 512 + col)), z = __builtin_nontemporal_load((const v4u*)(ZS + row * 512 + col));
;                     const f32x4 a0 = acc[ai][bj][m][0], a1 = acc[ai][bj][m][1];
;                     v4u w;
;                     w.x = pg8::cvt_pk_bf16(bflo(y.x) * sigm(a0[0] + b0[0]) * bflo(z.x), bfhi(y.x) * sigm(a0[1] + b0[1]) * bfhi(z.x));
;                     w.y = pg8::cvt_pk_bf16(bflo(y.y) * sigm(a0[2] + b0[2]) * bflo(z.y), bfhi(y.y) * sigm(a0[3] + b0[3]) * bfhi(z.y));
;                     w.z = pg8::cvt_pk_bf16(bflo(y.z) * sigm(a1[0] + b1[0]) * bflo(z.z), bfhi(y.z) * sigm(a1[1] + b1[1]) * bfhi(z.z));
;                     w.w = pg8::cvt_pk_bf16(bflo(y.w) * sigm(a1[2] + b1[2]) * bflo(z.w), bfhi(y.w) * sigm(a1[3] + b1[3]) * bfhi(z.w));
;                     *(v4u*)(A5 + row * 1024 + 512 + col) = w;
;                 }
;         }
	v_lshlrev_b32_e32 v146, 16, v202
	v_and_b32_e32 v147, 0xffff0000, v202
	v_lshlrev_b32_e32 v148, 16, v203
	v_and_b32_e32 v149, 0xffff0000, v203
	v_lshlrev_b32_e32 v150, 16, v204
	v_and_b32_e32 v151, 0xffff0000, v204
	v_lshlrev_b32_e32 v166, 16, v205
	v_and_b32_e32 v167, 0xffff0000, v205
	v_mul_f32_e32 v118, v118, v146
	v_mul_f32_e32 v119, v119, v147
	v_mul_f32_e32 v120, v120, v148
	v_mul_f32_e32 v121, v121, v149
	v_mul_f32_e32 v114, v114, v150
	v_mul_f32_e32 v115, v115, v151
	v_mul_f32_e32 v116, v116, v166
	v_mul_f32_e32 v117, v117, v167
	v_lshlrev_b32_e32 v146, 16, v206
	v_and_b32_e32 v147, 0xffff0000, v206
	v_lshlrev_b32_e32 v148, 16, v207
	v_and_b32_e32 v149, 0xffff0000, v207
	v_lshlrev_b32_e32 v150, 16, v208
	v_and_b32_e32 v151, 0xffff0000, v208
	v_lshlrev_b32_e32 v166, 16, v209
	v_and_b32_e32 v167, 0xffff0000, v209
	v_mul_f32_e32 v118, v118, v146
	v_mul_f32_e32 v119, v119, v147
	v_mul_f32_e32 v120, v120, v148
	v_mul_f32_e32 v121, v121, v149
	v_mul_f32_e32 v114, v114, v150
	v_mul_f32_e32 v115, v115, v151
	v_mul_f32_e32 v116, v116, v166
	v_mul_f32_e32 v117, v117, v167
	v_cvt_pk_bf16_f32 v138, v118, v119
	v_cvt_pk_bf16_f32 v139, v120, v121
	v_cvt_pk_bf16_f32 v140, v114, v115
	v_cvt_pk_bf16_f32 v141, v116, v117
	global_store_dwordx4 v[160:161], v[138:141], off offset:1024
	v_lshl_add_u64 v[160:161], v[160:161], 0, v[178:179]
	global_load_dwordx4 v[202:205], v[162:163], off offset:256 nt
	global_load_dwordx4 v[206:209], v[184:185], off offset:256 nt
	v_lshl_add_u64 v[162:163], v[162:163], 0, v[156:157]
	v_lshl_add_u64 v[184:185], v[184:185], 0, v[156:157]
	v_fmamk_f32 v102, v102, 0xbfb8aa3b, v110
	v_fmamk_f32 v103, v103, 0xbfb8aa3b, v111
	v_fmamk_f32 v104, v104, 0xbfb8aa3b, v112
	v_fmamk_f32 v105, v105, 0xbfb8aa3b, v113
	v_fmamk_f32 v98, v98, 0xbfb8aa3b, v106
	v_fmamk_f32 v99, v99, 0xbfb8aa3b, v107
	v_fmamk_f32 v100, v100, 0xbfb8aa3b, v108
	v_fmamk_f32 v101, v101, 0xbfb8aa3b, v109
	v_exp_f32_e32 v102, v102
	v_exp_f32_e32 v103, v103
	v_exp_f32_e32 v104, v104
	v_exp_f32_e32 v105, v105
	v_exp_f32_e32 v98, v98
	v_exp_f32_e32 v99, v99
	v_exp_f32_e32 v100, v100
	v_exp_f32_e32 v101, v101
	v_add_f32_e32 v102, 1.0, v102
	v_add_f32_e32 v103, 1.0, v103
	v_add_f32_e32 v104, 1.0, v104
	v_add_f32_e32 v105, 1.0, v105
	v_add_f32_e32 v98, 1.0, v98
	v_add_f32_e32 v99, 1.0, v99
	v_add_f32_e32 v100, 1.0, v100
	v_add_f32_e32 v101, 1.0, v101
	v_rcp_f32_e32 v102, v102
	v_rcp_f32_e32 v103, v103
	v_rcp_f32_e32 v104, v104
	v_rcp_f32_e32 v105, v105
	v_rcp_f32_e32 v98, v98
	v_rcp_f32_e32 v99, v99
	v_rcp_f32_e32 v100, v100
	v_rcp_f32_e32 v101, v101
	s_waitcnt vmcnt(17)
	v_lshlrev_b32_e32 v146, 16, v210
	v_and_b32_e32 v147, 0xffff0000, v210
	v_lshlrev_b32_e32 v148, 16, v211
	v_and_b32_e32 v149, 0xffff0000, v211
	v_lshlrev_b32_e32 v150, 16, v212
	v_and_b32_e32 v151, 0xffff0000, v212
	v_lshlrev_b32_e32 v166, 16, v213
	v_and_b32_e32 v167, 0xffff0000, v213
	v_mul_f32_e32 v102, v102, v146
	v_mul_f32_e32 v103, v103, v147
	v_mul_f32_e32 v104, v104, v148
	v_mul_f32_e32 v105, v105, v149
	v_mul_f32_e32 v98, v98, v150
	v_mul_f32_e32 v99, v99, v151
	v_mul_f32_e32 v100, v100, v166
	v_mul_f32_e32 v101, v101, v167
	v_lshlrev_b32_e32 v146, 16, v214
	v_and_b32_e32 v147, 0xffff0000, v214
	v_lshlrev_b32_e32 v148, 16, v215
	v_and_b32_e32 v149, 0xffff0000, v215
	v_lshlrev_b32_e32 v150, 16, v216
	v_and_b32_e32 v151, 0xffff0000, v216
	v_lshlrev_b32_e32 v166, 16, v217
	v_and_b32_e32 v167, 0xffff0000, v217
	v_mul_f32_e32 v102, v102, v146
	v_mul_f32_e32 v103, v103, v147
	v_mul_f32_e32 v104, v104, v148
	v_mul_f32_e32 v105, v105, v149
	v_mul_f32_e32 v98, v98, v150
	v_mul_f32_e32 v99, v99, v151
	v_mul_f32_e32 v100, v100, v166
	v_mul_f32_e32 v101, v101, v167
	v_cvt_pk_bf16_f32 v142, v102, v103
	v_cvt_pk_bf16_f32 v143, v104, v105
	v_cvt_pk_bf16_f32 v144, v98, v99
	v_cvt_pk_bf16_f32 v145, v100, v101
	global_store_dwordx4 v[160:161], v[142:145], off offset:1024
	v_lshl_add_u64 v[160:161], v[160:161], 0, v[180:181]
	global_load_dwordx4 v[210:213], v[162:163], off offset:256 nt
	global_load_dwordx4 v[214:217], v[184:185], off offset:256 nt
	v_lshl_add_u64 v[162:163], v[162:163], 0, v[158:159]
	v_lshl_add_u64 v[184:185], v[184:185], 0, v[158:159]
	v_fmamk_f32 v94, v94, 0xbfb8aa3b, v110
	v_fmamk_f32 v95, v95, 0xbfb8aa3b, v111
	v_fmamk_f32 v96, v96, 0xbfb8aa3b, v112
	v_fmamk_f32 v97, v97, 0xbfb8aa3b, v113
	v_fmamk_f32 v90, v90, 0xbfb8aa3b, v106
	v_fmamk_f32 v91, v91, 0xbfb8aa3b, v107
	v_fmamk_f32 v92, v92, 0xbfb8aa3b, v108
	v_fmamk_f32 v93, v93, 0xbfb8aa3b, v109
	v_exp_f32_e32 v94, v94
	v_exp_f32_e32 v95, v95
	v_exp_f32_e32 v96, v96
	v_exp_f32_e32 v97, v97
	v_exp_f32_e32 v90, v90
	v_exp_f32_e32 v91, v91
	v_exp_f32_e32 v92, v92
	v_exp_f32_e32 v93, v93
	v_add_f32_e32 v94, 1.0, v94
	v_add_f32_e32 v95, 1.0, v95
	v_add_f32_e32 v96, 1.0, v96
	v_add_f32_e32 v97, 1.0, v97
	v_add_f32_e32 v90, 1.0, v90
	v_add_f32_e32 v91, 1.0, v91
	v_add_f32_e32 v92, 1.0, v92
	v_add_f32_e32 v93, 1.0, v93
	v_rcp_f32_e32 v94, v94
	v_rcp_f32_e32 v95, v95
	v_rcp_f32_e32 v96, v96
	v_rcp_f32_e32 v97, v97
	v_rcp_f32_e32 v90, v90
	v_rcp_f32_e32 v91, v91
	v_rcp_f32_e32 v92, v92
	v_rcp_f32_e32 v93, v93
	s_waitcnt vmcnt(18)
; __device__ __forceinline__ unsigned cvt_pk_bf16(float lo, float hi) { unsigned r; asm volatile("v_cvt_pk_bf16_f32 %0, %1, %2" : "=v"(r) : "v"(lo), "v"(hi)); return r; }
; __device__ __forceinline__ float bflo(unsigned w) { return __uint_as_float(w << 16); }
; __device__ __forceinline__ float bfhi(unsigned w) { return __uint_as_float(w & 0xffff0000u); }
; __device__ __forceinline__ float sigm(float v) { return frcp(1.f + fexp2(-LOG2E * v)); }
;     __device__ __forceinline__ void operator()(const f32x4 (&acc)[2][2][4][2], const Unit& u, int wr, int wc, int fr, int fq) const {
;     ...
;         for (int bj = 0; bj < 2; ++bj) {
;             const int col = u.pn * 256 + bj * 128 + c8;
;             const f32x4 b0 = *(const f32x4*)(b_glu + col), b1 = *(const f32x4*)(b_glu + col + 4);
; #pragma unroll
;             for (int ai = 0; ai < 2; ++ai)
; #pragma unroll
;                 for (int m = 0; m < 4; ++m) {
;                     const size_t row = (size_t)(row0 + ai * 128 + m * 16);
;                     const v4u y = __builtin_nontemporal_load((const v4u*)(YG + row * 512 + col)), z = __builtin_nontemporal_load((const v4u*)(ZS + row * 512 + col));
;                     const f32x4 a0 = acc[ai][bj][m][0], a1 = acc[ai][bj][m][1];
;                     v4u w;
;                     w.x = pg8::cvt_pk_bf16(bflo(y.x) * sigm(a0[0] + b0[0]) * bflo(z.x), bfhi(y.x) * sigm(a0[1] + b0[1]) * bfhi(z.x));
;                     w.y = pg8::cvt_pk_bf16(bflo(y.y) * sigm(a0[2] + b0[2]) * bflo(z.y), bfhi(y.y) * sigm(a0[3] + b0[3]) * bfhi(z.y));
;                     w.z = pg8::cvt_pk_bf16(bflo(y.z) * sigm(a1[0] + b1[0]) * bflo(z.z), bfhi(y.z) * sigm(a1[1] + b1[1]) * bfhi(z.z));
;                     w.w = pg8::cvt_pk_bf16(bflo(y.w) * sigm(a1[2] + b1[2]) * bflo(z.w), bfhi(y.w) * sigm(a1[3] + b1[3]) * bfhi(z.w));
;                     *(v4u*)(A5 + row * 1024 + 512 + col) = w;
;                 }
;         }
	v_lshlrev_b32_e32 v146, 16, v218
	v_and_b32_e32 v147, 0xffff0000, v218
	v_lshlrev_b32_e32 v148, 16, v219
	v_and_b32_e32 v149, 0xffff0000, v219
	v_lshlrev_b32_e32 v150, 16, v220
	v_and_b32_e32 v151, 0xffff0000, v220
	v_lshlrev_b32_e32 v166, 16, v221
	v_and_b32_e32 v167, 0xffff0000, v221
	v_mul_f32_e32 v94, v94, v146
	v_mul_f32_e32 v95, v95, v147
	v_mul_f32_e32 v96, v96, v148
	v_mul_f32_e32 v97, v97, v149
	v_mul_f32_e32 v90, v90, v150
	v_mul_f32_e32 v91, v91, v151
	v_mul_f32_e32 v92, v92, v166
	v_mul_f32_e32 v93, v93, v167
	v_lshlrev_b32_e32 v146, 16, v222
	v_and_b32_e32 v147, 0xffff0000, v222
	v_lshlrev_b32_e32 v148, 16, v223
	v_and_b32_e32 v149, 0xffff0000, v223
	v_lshlrev_b32_e32 v150, 16, v224
	v_and_b32_e32 v151, 0xffff0000, v224
	v_lshlrev_b32_e32 v166, 16, v225
	v_and_b32_e32 v167, 0xffff0000, v225
	v_mul_f32_e32 v94, v94, v146
	v_mul_f32_e32 v95, v95, v147
	v_mul_f32_e32 v96, v96, v148
	v_mul_f32_e32 v97, v97, v149
	v_mul_f32_e32 v90, v90, v150
	v_mul_f32_e32 v91, v91, v151
	v_mul_f32_e32 v92, v92, v166
	v_mul_f32_e32 v93, v93, v167
	v_cvt_pk_bf16_f32 v138, v94, v95
	v_cvt_pk_bf16_f32 v139, v96, v97
	v_cvt_pk_bf16_f32 v140, v90, v91
	v_cvt_pk_bf16_f32 v141, v92, v93
	global_store_dwordx4 v[160:161], v[138:141], off offset:1024
	v_lshl_add_u64 v[160:161], v[160:161], 0, v[178:179]
	global_load_dwordx4 v[218:221], v[162:163], off offset:256 nt
	global_load_dwordx4 v[222:225], v[184:185], off offset:256 nt
	v_lshl_add_u64 v[162:163], v[162:163], 0, v[156:157]
	v_lshl_add_u64 v[184:185], v[184:185], 0, v[156:157]
	v_fmamk_f32 v86, v86, 0xbfb8aa3b, v110
	v_fmamk_f32 v87, v87, 0xbfb8aa3b, v111
	v_fmamk_f32 v88, v88, 0xbfb8aa3b, v112
	v_fmamk_f32 v89, v89, 0xbfb8aa3b, v113
	v_fmamk_f32 v82, v82, 0xbfb8aa3b, v106
	v_fmamk_f32 v83, v83, 0xbfb8aa3b, v107
	v_fmamk_f32 v84, v84, 0xbfb8aa3b, v108
	v_fmamk_f32 v85, v85, 0xbfb8aa3b, v109
	v_exp_f32_e32 v86, v86
	v_exp_f32_e32 v87, v87
	v_exp_f32_e32 v88, v88
	v_exp_f32_e32 v89, v89
	v_exp_f32_e32 v82, v82
	v_exp_f32_e32 v83, v83
	v_exp_f32_e32 v84, v84
	v_exp_f32_e32 v85, v85
	v_add_f32_e32 v86, 1.0, v86
	v_add_f32_e32 v87, 1.0, v87
	v_add_f32_e32 v88, 1.0, v88
	v_add_f32_e32 v89, 1.0, v89
	v_add_f32_e32 v82, 1.0, v82
	v_add_f32_e32 v83, 1.0, v83
	v_add_f32_e32 v84, 1.0, v84
	v_add_f32_e32 v85, 1.0, v85
	v_rcp_f32_e32 v86, v86
	v_rcp_f32_e32 v87, v87
	v_rcp_f32_e32 v88, v88
	v_rcp_f32_e32 v89, v89
	v_rcp_f32_e32 v82, v82
	v_rcp_f32_e32 v83, v83
	v_rcp_f32_e32 v84, v84
	v_rcp_f32_e32 v85, v85
	s_waitcnt vmcnt(19)
	v_lshlrev_b32_e32 v146, 16, v226
	v_and_b32_e32 v147, 0xffff0000, v226
	v_lshlrev_b32_e32 v148, 16, v227
	v_and_b32_e32 v149, 0xffff0000, v227
	v_lshlrev_b32_e32 v150, 16, v228
	v_and_b32_e32 v151, 0xffff0000, v228
	v_lshlrev_b32_e32 v166, 16, v229
	v_and_b32_e32 v167, 0xffff0000, v229
	v_mul_f32_e32 v86, v86, v146
	v_mul_f32_e32 v87, v87, v147
	v_mul_f32_e32 v88, v88, v148
	v_mul_f32_e32 v89, v89, v149
	v_mul_f32_e32 v82, v82, v150
	v_mul_f32_e32 v83, v83, v151
	v_mul_f32_e32 v84, v84, v166
	v_mul_f32_e32 v85, v85, v167
	v_lshlrev_b32_e32 v146, 16, v230
	v_and_b32_e32 v147, 0xffff0000, v230
	v_lshlrev_b32_e32 v148, 16, v231
	v_and_b32_e32 v149, 0xffff0000, v231
	v_lshlrev_b32_e32 v150, 16, v232
	v_and_b32_e32 v151, 0xffff0000, v232
	v_lshlrev_b32_e32 v166, 16, v233
	v_and_b32_e32 v167, 0xffff0000, v233
	v_mul_f32_e32 v86, v86, v146
	v_mul_f32_e32 v87, v87, v147
	v_mul_f32_e32 v88, v88, v148
	v_mul_f32_e32 v89, v89, v149
	v_mul_f32_e32 v82, v82, v150
	v_mul_f32_e32 v83, v83, v151
	v_mul_f32_e32 v84, v84, v166
	v_mul_f32_e32 v85, v85, v167
	v_cvt_pk_bf16_f32 v142, v86, v87
	v_cvt_pk_bf16_f32 v143, v88, v89
	v_cvt_pk_bf16_f32 v144, v82, v83
	v_cvt_pk_bf16_f32 v145, v84, v85
	global_store_dwordx4 v[160:161], v[142:145], off offset:1024
	v_lshl_add_u64 v[160:161], v[160:161], 0, v[178:179]
	global_load_dwordx4 v[226:229], v[162:163], off offset:256 nt
	global_load_dwordx4 v[230:233], v[184:185], off offset:256 nt
	v_lshl_add_u64 v[162:163], v[162:163], 0, v[156:157]
	v_lshl_add_u64 v[184:185], v[184:185], 0, v[156:157]
	v_fmamk_f32 v78, v78, 0xbfb8aa3b, v110
	v_fmamk_f32 v79, v79, 0xbfb8aa3b, v111
	v_fmamk_f32 v80, v80, 0xbfb8aa3b, v112
	v_fmamk_f32 v81, v81, 0xbfb8aa3b, v113
	v_fmamk_f32 v74, v74, 0xbfb8aa3b, v106
	v_fmamk_f32 v75, v75, 0xbfb8aa3b, v107
	v_fmamk_f32 v76, v76, 0xbfb8aa3b, v108
	v_fmamk_f32 v77, v77, 0xbfb8aa3b, v109
	v_exp_f32_e32 v78, v78
	v_exp_f32_e32 v79, v79
	v_exp_f32_e32 v80, v80
	v_exp_f32_e32 v81, v81
	v_exp_f32_e32 v74, v74
	v_exp_f32_e32 v75, v75
	v_exp_f32_e32 v76, v76
	v_exp_f32_e32 v77, v77
	v_add_f32_e32 v78, 1.0, v78
	v_add_f32_e32 v79, 1.0, v79
	v_add_f32_e32 v80, 1.0, v80
	v_add_f32_e32 v81, 1.0, v81
	v_add_f32_e32 v74, 1.0, v74
	v_add_f32_e32 v75, 1.0, v75
	v_add_f32_e32 v76, 1.0, v76
	v_add_f32_e32 v77, 1.0, v77
	v_rcp_f32_e32 v78, v78
	v_rcp_f32_e32 v79, v79
	v_rcp_f32_e32 v80, v80
	v_rcp_f32_e32 v81, v81
	v_rcp_f32_e32 v74, v74
	v_rcp_f32_e32 v75, v75
	v_rcp_f32_e32 v76, v76
	v_rcp_f32_e32 v77, v77
	s_waitcnt vmcnt(20)
; __device__ __forceinline__ unsigned cvt_pk_bf16(float lo, float hi) { unsigned r; asm volatile("v_cvt_pk_bf16_f32 %0, %1, %2" : "=v"(r) : "v"(lo), "v"(hi)); return r; }
; __device__ __forceinline__ float bflo(unsigned w) { return __uint_as_float(w << 16); }
; __device__ __forceinline__ float bfhi(unsigned w) { return __uint_as_float(w & 0xffff0000u); }
; __device__ __forceinline__ float sigm(float v) { return frcp(1.f + fexp2(-LOG2E * v)); }
;     __device__ __forceinline__ void operator()(const f32x4 (&acc)[2][2][4][2], const Unit& u, int wr, int wc, int fr, int fq) const {
;     ...
;         for (int bj = 0; bj < 2; ++bj) {
;             const int col = u.pn * 256 + bj * 128 + c8;
;             const f32x4 b0 = *(const f32x4*)(b_glu + col), b1 = *(const f32x4*)(b_glu + col + 4);
; #pragma unroll
;             for (int ai = 0; ai < 2; ++ai)
; #pragma unroll
;                 for (int m = 0; m < 4; ++m) {
;                     const size_t row = (size_t)(row0 + ai * 128 + m * 16);
;                     const v4u y = __builtin_nontemporal_load((const v4u*)(YG + row * 512 + col)), z = __builtin_nontemporal_load((const v4u*)(ZS + row * 512 + col));
;                     const f32x4 a0 = acc[ai][bj][m][0], a1 = acc[ai][bj][m][1];
;                     v4u w;
;                     w.x = pg8::cvt_pk_bf16(bflo(y.x) * sigm(a0[0] + b0[0]) * bflo(z.x), bfhi(y.x) * sigm(a0[1] + b0[1]) * bfhi(z.x));
;                     w.y = pg8::cvt_pk_bf16(bflo(y.y) * sigm(a0[2] + b0[2]) * bflo(z.y), bfhi(y.y) * sigm(a0[3] + b0[3]) * bfhi(z.y));
;                     w.z = pg8::cvt_pk_bf16(bflo(y.z) * sigm(a1[0] + b1[0]) * bflo(z.z), bfhi(y.z) * sigm(a1[1] + b1[1]) * bfhi(z.z));
;                     w.w = pg8::cvt_pk_bf16(bflo(y.w) * sigm(a1[2] + b1[2]) * bflo(z.w), bfhi(y.w) * sigm(a1[3] + b1[3]) * bfhi(z.w));
;                     *(v4u*)(A5 + row * 1024 + 512 + col) = w;
;                 }
;         }
	v_lshlrev_b32_e32 v146, 16, v234
	v_and_b32_e32 v147, 0xffff0000, v234
	v_lshlrev_b32_e32 v148, 16, v235
	v_and_b32_e32 v149, 0xffff0000, v235
	v_lshlrev_b32_e32 v150, 16, v236
	v_and_b32_e32 v151, 0xffff0000, v236
	v_lshlrev_b32_e32 v166, 16, v237
	v_and_b32_e32 v167, 0xffff0000, v237
	v_mul_f32_e32 v78, v78, v146
	v_mul_f32_e32 v79, v79, v147
	v_mul_f32_e32 v80, v80, v148
	v_mul_f32_e32 v81, v81, v149
	v_mul_f32_e32 v74, v74, v150
	v_mul_f32_e32 v75, v75, v151
	v_mul_f32_e32 v76, v76, v166
	v_mul_f32_e32 v77, v77, v167
	v_lshlrev_b32_e32 v146, 16, v238
	v_and_b32_e32 v147, 0xffff0000, v238
	v_lshlrev_b32_e32 v148, 16, v239
	v_and_b32_e32 v149, 0xffff0000, v239
	v_lshlrev_b32_e32 v150, 16, v240
	v_and_b32_e32 v151, 0xffff0000, v240
	v_lshlrev_b32_e32 v166, 16, v241
	v_and_b32_e32 v167, 0xffff0000, v241
	v_mul_f32_e32 v78, v78, v146
	v_mul_f32_e32 v79, v79, v147
	v_mul_f32_e32 v80, v80, v148
	v_mul_f32_e32 v81, v81, v149
	v_mul_f32_e32 v74, v74, v150
	v_mul_f32_e32 v75, v75, v151
	v_mul_f32_e32 v76, v76, v166
	v_mul_f32_e32 v77, v77, v167
	v_cvt_pk_bf16_f32 v138, v78, v79
	v_cvt_pk_bf16_f32 v139, v80, v81
	v_cvt_pk_bf16_f32 v140, v74, v75
	v_cvt_pk_bf16_f32 v141, v76, v77
	global_store_dwordx4 v[160:161], v[138:141], off offset:1024
	v_lshl_add_u64 v[160:161], v[160:161], 0, v[178:179]
	global_load_dwordx4 v[234:237], v[162:163], off offset:256 nt
	global_load_dwordx4 v[238:241], v[184:185], off offset:256 nt
	v_lshl_add_u64 v[162:163], v[162:163], 0, v[156:157]
	v_lshl_add_u64 v[184:185], v[184:185], 0, v[156:157]
	v_fmamk_f32 v70, v70, 0xbfb8aa3b, v110
	v_fmamk_f32 v71, v71, 0xbfb8aa3b, v111
	v_fmamk_f32 v72, v72, 0xbfb8aa3b, v112
	v_fmamk_f32 v73, v73, 0xbfb8aa3b, v113
	v_fmamk_f32 v66, v66, 0xbfb8aa3b, v106
	v_fmamk_f32 v67, v67, 0xbfb8aa3b, v107
	v_fmamk_f32 v68, v68, 0xbfb8aa3b, v108
	v_fmamk_f32 v69, v69, 0xbfb8aa3b, v109
	v_exp_f32_e32 v70, v70
	v_exp_f32_e32 v71, v71
	v_exp_f32_e32 v72, v72
	v_exp_f32_e32 v73, v73
	v_exp_f32_e32 v66, v66
	v_exp_f32_e32 v67, v67
	v_exp_f32_e32 v68, v68
	v_exp_f32_e32 v69, v69
	v_add_f32_e32 v70, 1.0, v70
	v_add_f32_e32 v71, 1.0, v71
	v_add_f32_e32 v72, 1.0, v72
	v_add_f32_e32 v73, 1.0, v73
	v_add_f32_e32 v66, 1.0, v66
	v_add_f32_e32 v67, 1.0, v67
	v_add_f32_e32 v68, 1.0, v68
	v_add_f32_e32 v69, 1.0, v69
	v_rcp_f32_e32 v70, v70
	v_rcp_f32_e32 v71, v71
	v_rcp_f32_e32 v72, v72
	v_rcp_f32_e32 v73, v73
	v_rcp_f32_e32 v66, v66
	v_rcp_f32_e32 v67, v67
	v_rcp_f32_e32 v68, v68
	v_rcp_f32_e32 v69, v69
	s_waitcnt vmcnt(21)
	v_lshlrev_b32_e32 v146, 16, v242
	v_and_b32_e32 v147, 0xffff0000, v242
	v_lshlrev_b32_e32 v148, 16, v243
	v_and_b32_e32 v149, 0xffff0000, v243
	v_lshlrev_b32_e32 v150, 16, v244
	v_and_b32_e32 v151, 0xffff0000, v244
	v_lshlrev_b32_e32 v166, 16, v245
	v_and_b32_e32 v167, 0xffff0000, v245
	v_mul_f32_e32 v70, v70, v146
	v_mul_f32_e32 v71, v71, v147
	v_mul_f32_e32 v72, v72, v148
	v_mul_f32_e32 v73, v73, v149
	v_mul_f32_e32 v66, v66, v150
	v_mul_f32_e32 v67, v67, v151
	v_mul_f32_e32 v68, v68, v166
	v_mul_f32_e32 v69, v69, v167
	v_lshlrev_b32_e32 v146, 16, v246
	v_and_b32_e32 v147, 0xffff0000, v246
	v_lshlrev_b32_e32 v148, 16, v247
	v_and_b32_e32 v149, 0xffff0000, v247
	v_lshlrev_b32_e32 v150, 16, v248
	v_and_b32_e32 v151, 0xffff0000, v248
	v_lshlrev_b32_e32 v166, 16, v249
	v_and_b32_e32 v167, 0xffff0000, v249
	v_mul_f32_e32 v70, v70, v146
	v_mul_f32_e32 v71, v71, v147
	v_mul_f32_e32 v72, v72, v148
	v_mul_f32_e32 v73, v73, v149
	v_mul_f32_e32 v66, v66, v150
	v_mul_f32_e32 v67, v67, v151
	v_mul_f32_e32 v68, v68, v166
	v_mul_f32_e32 v69, v69, v167
	v_cvt_pk_bf16_f32 v142, v70, v71
	v_cvt_pk_bf16_f32 v143, v72, v73
	v_cvt_pk_bf16_f32 v144, v66, v67
	v_cvt_pk_bf16_f32 v145, v68, v69
	global_store_dwordx4 v[160:161], v[142:145], off offset:1024
	global_load_dwordx4 v[242:245], v[162:163], off offset:256 nt
	global_load_dwordx4 v[246:249], v[184:185], off offset:256 nt
	v_fmamk_f32 v62, v62, 0xbfb8aa3b, v170
	v_fmamk_f32 v63, v63, 0xbfb8aa3b, v171
	v_fmamk_f32 v64, v64, 0xbfb8aa3b, v172
	v_fmamk_f32 v65, v65, 0xbfb8aa3b, v173
	v_fmamk_f32 v58, v58, 0xbfb8aa3b, v174
	v_fmamk_f32 v59, v59, 0xbfb8aa3b, v175
	v_fmamk_f32 v60, v60, 0xbfb8aa3b, v176
	v_fmamk_f32 v61, v61, 0xbfb8aa3b, v177
	v_exp_f32_e32 v62, v62
	v_exp_f32_e32 v63, v63
	v_exp_f32_e32 v64, v64
	v_exp_f32_e32 v65, v65
	v_exp_f32_e32 v58, v58
	v_exp_f32_e32 v59, v59
	v_exp_f32_e32 v60, v60
	v_exp_f32_e32 v61, v61
	v_add_f32_e32 v62, 1.0, v62
	v_add_f32_e32 v63, 1.0, v63
	v_add_f32_e32 v64, 1.0, v64
	v_add_f32_e32 v65, 1.0, v65
	v_add_f32_e32 v58, 1.0, v58
	v_add_f32_e32 v59, 1.0, v59
	v_add_f32_e32 v60, 1.0, v60
	v_add_f32_e32 v61, 1.0, v61
	v_rcp_f32_e32 v62, v62
	v_rcp_f32_e32 v63, v63
	v_rcp_f32_e32 v64, v64
	v_rcp_f32_e32 v65, v65
	v_rcp_f32_e32 v58, v58
	v_rcp_f32_e32 v59, v59
	v_rcp_f32_e32 v60, v60
	v_rcp_f32_e32 v61, v61
	s_waitcnt vmcnt(21)
; __device__ __forceinline__ unsigned cvt_pk_bf16(float lo, float hi) { unsigned r; asm volatile("v_cvt_pk_bf16_f32 %0, %1, %2" : "=v"(r) : "v"(lo), "v"(hi)); return r; }
; __device__ __forceinline__ float bflo(unsigned w) { return __uint_as_float(w << 16); }
; __device__ __forceinline__ float bfhi(unsigned w) { return __uint_as_float(w & 0xffff0000u); }
; __device__ __forceinline__ float sigm(float v) { return frcp(1.f + fexp2(-LOG2E * v)); }
;     __device__ __forceinline__ void operator()(const f32x4 (&acc)[2][2][4][2], const Unit& u, int wr, int wc, int fr, int fq) const {
;     ...
;         for (int bj = 0; bj < 2; ++bj) {
;             const int col = u.pn * 256 + bj * 128 + c8;
;             const f32x4 b0 = *(const f32x4*)(b_glu + col), b1 = *(const f32x4*)(b_glu + col + 4);
; #pragma unroll
;             for (int ai = 0; ai < 2; ++ai)
; #pragma unroll
;                 for (int m = 0; m < 4; ++m) {
;                     const size_t row = (size_t)(row0 + ai * 128 + m * 16);
;                     const v4u y = __builtin_nontemporal_load((const v4u*)(YG + row * 512 + col)), z = __builtin_nontemporal_load((const v4u*)(ZS + row * 512 + col));
;                     const f32x4 a0 = acc[ai][bj][m][0], a1 = acc[ai][bj][m][1];
;                     v4u w;
;                     w.x = pg8::cvt_pk_bf16(bflo(y.x) * sigm(a0[0] + b0[0]) * bflo(z.x), bfhi(y.x) * sigm(a0[1] + b0[1]) * bfhi(z.x));
;                     w.y = pg8::cvt_pk_bf16(bflo(y.y) * sigm(a0[2] + b0[2]) * bflo(z.y), bfhi(y.y) * sigm(a0[3] + b0[3]) * bfhi(z.y));
;                     w.z = pg8::cvt_pk_bf16(bflo(y.z) * sigm(a1[0] + b1[0]) * bflo(z.z), bfhi(y.z) * sigm(a1[1] + b1[1]) * bfhi(z.z));
;                     w.w = pg8::cvt_pk_bf16(bflo(y.w) * sigm(a1[2] + b1[2]) * bflo(z.w), bfhi(y.w) * sigm(a1[3] + b1[3]) * bfhi(z.w));
;                     *(v4u*)(A5 + row * 1024 + 512 + col) = w;
;                 }
;         }
	v_lshlrev_b32_e32 v146, 16, v186
	v_and_b32_e32 v147, 0xffff0000, v186
	v_lshlrev_b32_e32 v148, 16, v187
	v_and_b32_e32 v149, 0xffff0000, v187
	v_lshlrev_b32_e32 v150, 16, v188
	v_and_b32_e32 v151, 0xffff0000, v188
	v_lshlrev_b32_e32 v166, 16, v189
	v_and_b32_e32 v167, 0xffff0000, v189
	v_mul_f32_e32 v62, v62, v146
	v_mul_f32_e32 v63, v63, v147
	v_mul_f32_e32 v64, v64, v148
	v_mul_f32_e32 v65, v65, v149
	v_mul_f32_e32 v58, v58, v150
	v_mul_f32_e32 v59, v59, v151
	v_mul_f32_e32 v60, v60, v166
	v_mul_f32_e32 v61, v61, v167
	v_lshlrev_b32_e32 v146, 16, v190
	v_and_b32_e32 v147, 0xffff0000, v190
	v_lshlrev_b32_e32 v148, 16, v191
	v_and_b32_e32 v149, 0xffff0000, v191
	v_lshlrev_b32_e32 v150, 16, v192
	v_and_b32_e32 v151, 0xffff0000, v192
	v_lshlrev_b32_e32 v166, 16, v193
	v_and_b32_e32 v167, 0xffff0000, v193
	v_mul_f32_e32 v62, v62, v146
	v_mul_f32_e32 v63, v63, v147
	v_mul_f32_e32 v64, v64, v148
	v_mul_f32_e32 v65, v65, v149
	v_mul_f32_e32 v58, v58, v150
	v_mul_f32_e32 v59, v59, v151
	v_mul_f32_e32 v60, v60, v166
	v_mul_f32_e32 v61, v61, v167
	v_cvt_pk_bf16_f32 v138, v62, v63
	v_cvt_pk_bf16_f32 v139, v64, v65
	v_cvt_pk_bf16_f32 v140, v58, v59
	v_cvt_pk_bf16_f32 v141, v60, v61
	global_store_dwordx4 v[182:183], v[138:141], off offset:1280
	v_lshl_add_u64 v[182:183], v[182:183], 0, v[178:179]
	v_fmamk_f32 v54, v54, 0xbfb8aa3b, v170
	v_fmamk_f32 v55, v55, 0xbfb8aa3b, v171
	v_fmamk_f32 v56, v56, 0xbfb8aa3b, v172
	v_fmamk_f32 v57, v57, 0xbfb8aa3b, v173
	v_fmamk_f32 v50, v50, 0xbfb8aa3b, v174
	v_fmamk_f32 v51, v51, 0xbfb8aa3b, v175
	v_fmamk_f32 v52, v52, 0xbfb8aa3b, v176
	v_fmamk_f32 v53, v53, 0xbfb8aa3b, v177
	v_exp_f32_e32 v54, v54
	v_exp_f32_e32 v55, v55
	v_exp_f32_e32 v56, v56
	v_exp_f32_e32 v57, v57
	v_exp_f32_e32 v50, v50
	v_exp_f32_e32 v51, v51
	v_exp_f32_e32 v52, v52
	v_exp_f32_e32 v53, v53
	v_add_f32_e32 v54, 1.0, v54
	v_add_f32_e32 v55, 1.0, v55
	v_add_f32_e32 v56, 1.0, v56
	v_add_f32_e32 v57, 1.0, v57
	v_add_f32_e32 v50, 1.0, v50
	v_add_f32_e32 v51, 1.0, v51
	v_add_f32_e32 v52, 1.0, v52
	v_add_f32_e32 v53, 1.0, v53
	v_rcp_f32_e32 v54, v54
	v_rcp_f32_e32 v55, v55
	v_rcp_f32_e32 v56, v56
	v_rcp_f32_e32 v57, v57
	v_rcp_f32_e32 v50, v50
	v_rcp_f32_e32 v51, v51
	v_rcp_f32_e32 v52, v52
	v_rcp_f32_e32 v53, v53
	s_waitcnt vmcnt(19)
	v_lshlrev_b32_e32 v146, 16, v194
	v_and_b32_e32 v147, 0xffff0000, v194
	v_lshlrev_b32_e32 v148, 16, v195
	v_and_b32_e32 v149, 0xffff0000, v195
	v_lshlrev_b32_e32 v150, 16, v196
	v_and_b32_e32 v151, 0xffff0000, v196
	v_lshlrev_b32_e32 v166, 16, v197
	v_and_b32_e32 v167, 0xffff0000, v197
	v_mul_f32_e32 v54, v54, v146
	v_mul_f32_e32 v55, v55, v147
	v_mul_f32_e32 v56, v56, v148
	v_mul_f32_e32 v57, v57, v149
	v_mul_f32_e32 v50, v50, v150
	v_mul_f32_e32 v51, v51, v151
	v_mul_f32_e32 v52, v52, v166
	v_mul_f32_e32 v53, v53, v167
	v_lshlrev_b32_e32 v146, 16, v198
	v_and_b32_e32 v147, 0xffff0000, v198
	v_lshlrev_b32_e32 v148, 16, v199
	v_and_b32_e32 v149, 0xffff0000, v199
	v_lshlrev_b32_e32 v150, 16, v200
	v_and_b32_e32 v151, 0xffff0000, v200
	v_lshlrev_b32_e32 v166, 16, v201
	v_and_b32_e32 v167, 0xffff0000, v201
	v_mul_f32_e32 v54, v54, v146
	v_mul_f32_e32 v55, v55, v147
	v_mul_f32_e32 v56, v56, v148
	v_mul_f32_e32 v57, v57, v149
	v_mul_f32_e32 v50, v50, v150
	v_mul_f32_e32 v51, v51, v151
	v_mul_f32_e32 v52, v52, v166
	v_mul_f32_e32 v53, v53, v167
	v_cvt_pk_bf16_f32 v142, v54, v55
	v_cvt_pk_bf16_f32 v143, v56, v57
	v_cvt_pk_bf16_f32 v144, v50, v51
	v_cvt_pk_bf16_f32 v145, v52, v53
	global_store_dwordx4 v[182:183], v[142:145], off offset:1280
	v_lshl_add_u64 v[182:183], v[182:183], 0, v[178:179]
	v_fmamk_f32 v46, v46, 0xbfb8aa3b, v170
	v_fmamk_f32 v47, v47, 0xbfb8aa3b, v171
	v_fmamk_f32 v48, v48, 0xbfb8aa3b, v172
	v_fmamk_f32 v49, v49, 0xbfb8aa3b, v173
	v_fmamk_f32 v42, v42, 0xbfb8aa3b, v174
	v_fmamk_f32 v43, v43, 0xbfb8aa3b, v175
	v_fmamk_f32 v44, v44, 0xbfb8aa3b, v176
	v_fmamk_f32 v45, v45, 0xbfb8aa3b, v177
	v_exp_f32_e32 v46, v46
	v_exp_f32_e32 v47, v47
	v_exp_f32_e32 v48, v48
	v_exp_f32_e32 v49, v49
	v_exp_f32_e32 v42, v42
	v_exp_f32_e32 v43, v43
	v_exp_f32_e32 v44, v44
	v_exp_f32_e32 v45, v45
	v_add_f32_e32 v46, 1.0, v46
	v_add_f32_e32 v47, 1.0, v47
	v_add_f32_e32 v48, 1.0, v48
	v_add_f32_e32 v49, 1.0, v49
	v_add_f32_e32 v42, 1.0, v42
	v_add_f32_e32 v43, 1.0, v43
	v_add_f32_e32 v44, 1.0, v44
	v_add_f32_e32 v45, 1.0, v45
	v_rcp_f32_e32 v46, v46
	v_rcp_f32_e32 v47, v47
	v_rcp_f32_e32 v48, v48
	v_rcp_f32_e32 v49, v49
	v_rcp_f32_e32 v42, v42
	v_rcp_f32_e32 v43, v43
	v_rcp_f32_e32 v44, v44
	v_rcp_f32_e32 v45, v45
	s_waitcnt vmcnt(17)
; __device__ __forceinline__ unsigned cvt_pk_bf16(float lo, float hi) { unsigned r; asm volatile("v_cvt_pk_bf16_f32 %0, %1, %2" : "=v"(r) : "v"(lo), "v"(hi)); return r; }
; __device__ __forceinline__ float bflo(unsigned w) { return __uint_as_float(w << 16); }
; __device__ __forceinline__ float bfhi(unsigned w) { return __uint_as_float(w & 0xffff0000u); }
; __device__ __forceinline__ float sigm(float v) { return frcp(1.f + fexp2(-LOG2E * v)); }
;     __device__ __forceinline__ void operator()(const f32x4 (&acc)[2][2][4][2], const Unit& u, int wr, int wc, int fr, int fq) const {
;     ...
;         for (int bj = 0; bj < 2; ++bj) {
;             const int col = u.pn * 256 + bj * 128 + c8;
;             const f32x4 b0 = *(const f32x4*)(b_glu + col), b1 = *(const f32x4*)(b_glu + col + 4);
; #pragma unroll
;             for (int ai = 0; ai < 2; ++ai)
; #pragma unroll
;                 for (int m = 0; m < 4; ++m) {
;                     const size_t row = (size_t)(row0 + ai * 128 + m * 16);
;                     const v4u y = __builtin_nontemporal_load((const v4u*)(YG + row * 512 + col)), z = __builtin_nontemporal_load((const v4u*)(ZS + row * 512 + col));
;                     const f32x4 a0 = acc[ai][bj][m][0], a1 = acc[ai][bj][m][1];
;                     v4u w;
;                     w.x = pg8::cvt_pk_bf16(bflo(y.x) * sigm(a0[0] + b0[0]) * bflo(z.x), bfhi(y.x) * sigm(a0[1] + b0[1]) * bfhi(z.x));
;                     w.y = pg8::cvt_pk_bf16(bflo(y.y) * sigm(a0[2] + b0[2]) * bflo(z.y), bfhi(y.y) * sigm(a0[3] + b0[3]) * bfhi(z.y));
;                     w.z = pg8::cvt_pk_bf16(bflo(y.z) * sigm(a1[0] + b1[0]) * bflo(z.z), bfhi(y.z) * sigm(a1[1] + b1[1]) * bfhi(z.z));
;                     w.w = pg8::cvt_pk_bf16(bflo(y.w) * sigm(a1[2] + b1[2]) * bflo(z.w), bfhi(y.w) * sigm(a1[3] + b1[3]) * bfhi(z.w));
;                     *(v4u*)(A5 + row * 1024 + 512 + col) = w;
;                 }
;         }
	v_lshlrev_b32_e32 v146, 16, v202
	v_and_b32_e32 v147, 0xffff0000, v202
	v_lshlrev_b32_e32 v148, 16, v203
	v_and_b32_e32 v149, 0xffff0000, v203
	v_lshlrev_b32_e32 v150, 16, v204
	v_and_b32_e32 v151, 0xffff0000, v204
	v_lshlrev_b32_e32 v166, 16, v205
	v_and_b32_e32 v167, 0xffff0000, v205
	v_mul_f32_e32 v46, v46, v146
	v_mul_f32_e32 v47, v47, v147
	v_mul_f32_e32 v48, v48, v148
	v_mul_f32_e32 v49, v49, v149
	v_mul_f32_e32 v42, v42, v150
	v_mul_f32_e32 v43, v43, v151
	v_mul_f32_e32 v44, v44, v166
	v_mul_f32_e32 v45, v45, v167
	v_lshlrev_b32_e32 v146, 16, v206
	v_and_b32_e32 v147, 0xffff0000, v206
	v_lshlrev_b32_e32 v148, 16, v207
	v_and_b32_e32 v149, 0xffff0000, v207
	v_lshlrev_b32_e32 v150, 16, v208
	v_and_b32_e32 v151, 0xffff0000, v208
	v_lshlrev_b32_e32 v166, 16, v209
	v_and_b32_e32 v167, 0xffff0000, v209
	v_mul_f32_e32 v46, v46, v146
	v_mul_f32_e32 v47, v47, v147
	v_mul_f32_e32 v48, v48, v148
	v_mul_f32_e32 v49, v49, v149
	v_mul_f32_e32 v42, v42, v150
	v_mul_f32_e32 v43, v43, v151
	v_mul_f32_e32 v44, v44, v166
	v_mul_f32_e32 v45, v45, v167
	v_cvt_pk_bf16_f32 v138, v46, v47
	v_cvt_pk_bf16_f32 v139, v48, v49
	v_cvt_pk_bf16_f32 v140, v42, v43
	v_cvt_pk_bf16_f32 v141, v44, v45
	global_store_dwordx4 v[182:183], v[138:141], off offset:1280
	v_lshl_add_u64 v[182:183], v[182:183], 0, v[178:179]
	v_fmamk_f32 v38, v38, 0xbfb8aa3b, v170
	v_fmamk_f32 v39, v39, 0xbfb8aa3b, v171
	v_fmamk_f32 v40, v40, 0xbfb8aa3b, v172
	v_fmamk_f32 v41, v41, 0xbfb8aa3b, v173
	v_fmamk_f32 v34, v34, 0xbfb8aa3b, v174
	v_fmamk_f32 v35, v35, 0xbfb8aa3b, v175
	v_fmamk_f32 v36, v36, 0xbfb8aa3b, v176
	v_fmamk_f32 v37, v37, 0xbfb8aa3b, v177
	v_exp_f32_e32 v38, v38
	v_exp_f32_e32 v39, v39
	v_exp_f32_e32 v40, v40
	v_exp_f32_e32 v41, v41
	v_exp_f32_e32 v34, v34
	v_exp_f32_e32 v35, v35
	v_exp_f32_e32 v36, v36
	v_exp_f32_e32 v37, v37
	v_add_f32_e32 v38, 1.0, v38
	v_add_f32_e32 v39, 1.0, v39
	v_add_f32_e32 v40, 1.0, v40
	v_add_f32_e32 v41, 1.0, v41
	v_add_f32_e32 v34, 1.0, v34
	v_add_f32_e32 v35, 1.0, v35
	v_add_f32_e32 v36, 1.0, v36
	v_add_f32_e32 v37, 1.0, v37
	v_rcp_f32_e32 v38, v38
	v_rcp_f32_e32 v39, v39
	v_rcp_f32_e32 v40, v40
	v_rcp_f32_e32 v41, v41
	v_rcp_f32_e32 v34, v34
	v_rcp_f32_e32 v35, v35
	v_rcp_f32_e32 v36, v36
	v_rcp_f32_e32 v37, v37
	s_waitcnt vmcnt(15)
	v_lshlrev_b32_e32 v146, 16, v210
	v_and_b32_e32 v147, 0xffff0000, v210
	v_lshlrev_b32_e32 v148, 16, v211
	v_and_b32_e32 v149, 0xffff0000, v211
	v_lshlrev_b32_e32 v150, 16, v212
	v_and_b32_e32 v151, 0xffff0000, v212
	v_lshlrev_b32_e32 v166, 16, v213
	v_and_b32_e32 v167, 0xffff0000, v213
	v_mul_f32_e32 v38, v38, v146
	v_mul_f32_e32 v39, v39, v147
	v_mul_f32_e32 v40, v40, v148
	v_mul_f32_e32 v41, v41, v149
	v_mul_f32_e32 v34, v34, v150
	v_mul_f32_e32 v35, v35, v151
	v_mul_f32_e32 v36, v36, v166
	v_mul_f32_e32 v37, v37, v167
	v_lshlrev_b32_e32 v146, 16, v214
	v_and_b32_e32 v147, 0xffff0000, v214
	v_lshlrev_b32_e32 v148, 16, v215
	v_and_b32_e32 v149, 0xffff0000, v215
	v_lshlrev_b32_e32 v150, 16, v216
	v_and_b32_e32 v151, 0xffff0000, v216
	v_lshlrev_b32_e32 v166, 16, v217
	v_and_b32_e32 v167, 0xffff0000, v217
	v_mul_f32_e32 v38, v38, v146
	v_mul_f32_e32 v39, v39, v147
	v_mul_f32_e32 v40, v40, v148
	v_mul_f32_e32 v41, v41, v149
	v_mul_f32_e32 v34, v34, v150
	v_mul_f32_e32 v35, v35, v151
	v_mul_f32_e32 v36, v36, v166
	v_mul_f32_e32 v37, v37, v167
	v_cvt_pk_bf16_f32 v142, v38, v39
	v_cvt_pk_bf16_f32 v143, v40, v41
	v_cvt_pk_bf16_f32 v144, v34, v35
	v_cvt_pk_bf16_f32 v145, v36, v37
	global_store_dwordx4 v[182:183], v[142:145], off offset:1280
	v_lshl_add_u64 v[182:183], v[182:183], 0, v[180:181]
	v_fmamk_f32 v30, v30, 0xbfb8aa3b, v170
	v_fmamk_f32 v31, v31, 0xbfb8aa3b, v171
	v_fmamk_f32 v32, v32, 0xbfb8aa3b, v172
	v_fmamk_f32 v33, v33, 0xbfb8aa3b, v173
	v_fmamk_f32 v26, v26, 0xbfb8aa3b, v174
	v_fmamk_f32 v27, v27, 0xbfb8aa3b, v175
	v_fmamk_f32 v28, v28, 0xbfb8aa3b, v176
	v_fmamk_f32 v29, v29, 0xbfb8aa3b, v177
	v_exp_f32_e32 v30, v30
	v_exp_f32_e32 v31, v31
	v_exp_f32_e32 v32, v32
	v_exp_f32_e32 v33, v33
	v_exp_f32_e32 v26, v26
	v_exp_f32_e32 v27, v27
	v_exp_f32_e32 v28, v28
	v_exp_f32_e32 v29, v29
	v_add_f32_e32 v30, 1.0, v30
	v_add_f32_e32 v31, 1.0, v31
	v_add_f32_e32 v32, 1.0, v32
	v_add_f32_e32 v33, 1.0, v33
	v_add_f32_e32 v26, 1.0, v26
	v_add_f32_e32 v27, 1.0, v27
	v_add_f32_e32 v28, 1.0, v28
	v_add_f32_e32 v29, 1.0, v29
	v_rcp_f32_e32 v30, v30
	v_rcp_f32_e32 v31, v31
	v_rcp_f32_e32 v32, v32
	v_rcp_f32_e32 v33, v33
	v_rcp_f32_e32 v26, v26
	v_rcp_f32_e32 v27, v27
	v_rcp_f32_e32 v28, v28
	v_rcp_f32_e32 v29, v29
	s_waitcnt vmcnt(13)
; __device__ __forceinline__ unsigned cvt_pk_bf16(float lo, float hi) { unsigned r; asm volatile("v_cvt_pk_bf16_f32 %0, %1, %2" : "=v"(r) : "v"(lo), "v"(hi)); return r; }
; __device__ __forceinline__ float bflo(unsigned w) { return __uint_as_float(w << 16); }
; __device__ __forceinline__ float bfhi(unsigned w) { return __uint_as_float(w & 0xffff0000u); }
; __device__ __forceinline__ float sigm(float v) { return frcp(1.f + fexp2(-LOG2E * v)); }
;     __device__ __forceinline__ void operator()(const f32x4 (&acc)[2][2][4][2], const Unit& u, int wr, int wc, int fr, int fq) const {
;     ...
;         for (int bj = 0; bj < 2; ++bj) {
;             const int col = u.pn * 256 + bj * 128 + c8;
;             const f32x4 b0 = *(const f32x4*)(b_glu + col), b1 = *(const f32x4*)(b_glu + col + 4);
; #pragma unroll
;             for (int ai = 0; ai < 2; ++ai)
; #pragma unroll
;                 for (int m = 0; m < 4; ++m) {
;                     const size_t row = (size_t)(row0 + ai * 128 + m * 16);
;                     const v4u y = __builtin_nontemporal_load((const v4u*)(YG + row * 512 + col)), z = __builtin_nontemporal_load((const v4u*)(ZS + row * 512 + col));
;                     const f32x4 a0 = acc[ai][bj][m][0], a1 = acc[ai][bj][m][1];
;                     v4u w;
;                     w.x = pg8::cvt_pk_bf16(bflo(y.x) * sigm(a0[0] + b0[0]) * bflo(z.x), bfhi(y.x) * sigm(a0[1] + b0[1]) * bfhi(z.x));
;                     w.y = pg8::cvt_pk_bf16(bflo(y.y) * sigm(a0[2] + b0[2]) * bflo(z.y), bfhi(y.y) * sigm(a0[3] + b0[3]) * bfhi(z.y));
;                     w.z = pg8::cvt_pk_bf16(bflo(y.z) * sigm(a1[0] + b1[0]) * bflo(z.z), bfhi(y.z) * sigm(a1[1] + b1[1]) * bfhi(z.z));
;                     w.w = pg8::cvt_pk_bf16(bflo(y.w) * sigm(a1[2] + b1[2]) * bflo(z.w), bfhi(y.w) * sigm(a1[3] + b1[3]) * bfhi(z.w));
;                     *(v4u*)(A5 + row * 1024 + 512 + col) = w;
;                 }
;         }
	v_lshlrev_b32_e32 v146, 16, v218
	v_and_b32_e32 v147, 0xffff0000, v218
	v_lshlrev_b32_e32 v148, 16, v219
	v_and_b32_e32 v149, 0xffff0000, v219
	v_lshlrev_b32_e32 v150, 16, v220
	v_and_b32_e32 v151, 0xffff0000, v220
	v_lshlrev_b32_e32 v166, 16, v221
	v_and_b32_e32 v167, 0xffff0000, v221
	v_mul_f32_e32 v30, v30, v146
	v_mul_f32_e32 v31, v31, v147
	v_mul_f32_e32 v32, v32, v148
	v_mul_f32_e32 v33, v33, v149
	v_mul_f32_e32 v26, v26, v150
	v_mul_f32_e32 v27, v27, v151
	v_mul_f32_e32 v28, v28, v166
	v_mul_f32_e32 v29, v29, v167
	v_lshlrev_b32_e32 v146, 16, v222
	v_and_b32_e32 v147, 0xffff0000, v222
	v_lshlrev_b32_e32 v148, 16, v223
	v_and_b32_e32 v149, 0xffff0000, v223
	v_lshlrev_b32_e32 v150, 16, v224
	v_and_b32_e32 v151, 0xffff0000, v224
	v_lshlrev_b32_e32 v166, 16, v225
	v_and_b32_e32 v167, 0xffff0000, v225
	v_mul_f32_e32 v30, v30, v146
	v_mul_f32_e32 v31, v31, v147
	v_mul_f32_e32 v32, v32, v148
	v_mul_f32_e32 v33, v33, v149
	v_mul_f32_e32 v26, v26, v150
	v_mul_f32_e32 v27, v27, v151
	v_mul_f32_e32 v28, v28, v166
	v_mul_f32_e32 v29, v29, v167
	v_cvt_pk_bf16_f32 v138, v30, v31
	v_cvt_pk_bf16_f32 v139, v32, v33
	v_cvt_pk_bf16_f32 v140, v26, v27
	v_cvt_pk_bf16_f32 v141, v28, v29
	global_store_dwordx4 v[182:183], v[138:141], off offset:1280
	v_lshl_add_u64 v[182:183], v[182:183], 0, v[178:179]
	v_fmamk_f32 v22, v22, 0xbfb8aa3b, v170
	v_fmamk_f32 v23, v23, 0xbfb8aa3b, v171
	v_fmamk_f32 v24, v24, 0xbfb8aa3b, v172
	v_fmamk_f32 v25, v25, 0xbfb8aa3b, v173
	v_fmamk_f32 v18, v18, 0xbfb8aa3b, v174
	v_fmamk_f32 v19, v19, 0xbfb8aa3b, v175
	v_fmamk_f32 v20, v20, 0xbfb8aa3b, v176
	v_fmamk_f32 v21, v21, 0xbfb8aa3b, v177
	v_exp_f32_e32 v22, v22
	v_exp_f32_e32 v23, v23
	v_exp_f32_e32 v24, v24
	v_exp_f32_e32 v25, v25
	v_exp_f32_e32 v18, v18
	v_exp_f32_e32 v19, v19
	v_exp_f32_e32 v20, v20
	v_exp_f32_e32 v21, v21
	v_add_f32_e32 v22, 1.0, v22
	v_add_f32_e32 v23, 1.0, v23
	v_add_f32_e32 v24, 1.0, v24
	v_add_f32_e32 v25, 1.0, v25
	v_add_f32_e32 v18, 1.0, v18
	v_add_f32_e32 v19, 1.0, v19
	v_add_f32_e32 v20, 1.0, v20
	v_add_f32_e32 v21, 1.0, v21
	v_rcp_f32_e32 v22, v22
	v_rcp_f32_e32 v23, v23
	v_rcp_f32_e32 v24, v24
	v_rcp_f32_e32 v25, v25
	v_rcp_f32_e32 v18, v18
	v_rcp_f32_e32 v19, v19
	v_rcp_f32_e32 v20, v20
	v_rcp_f32_e32 v21, v21
	s_waitcnt vmcnt(11)
	v_lshlrev_b32_e32 v146, 16, v226
	v_and_b32_e32 v147, 0xffff0000, v226
	v_lshlrev_b32_e32 v148, 16, v227
	v_and_b32_e32 v149, 0xffff0000, v227
	v_lshlrev_b32_e32 v150, 16, v228
	v_and_b32_e32 v151, 0xffff0000, v228
	v_lshlrev_b32_e32 v166, 16, v229
	v_and_b32_e32 v167, 0xffff0000, v229
	v_mul_f32_e32 v22, v22, v146
	v_mul_f32_e32 v23, v23, v147
	v_mul_f32_e32 v24, v24, v148
	v_mul_f32_e32 v25, v25, v149
	v_mul_f32_e32 v18, v18, v150
	v_mul_f32_e32 v19, v19, v151
	v_mul_f32_e32 v20, v20, v166
	v_mul_f32_e32 v21, v21, v167
	v_lshlrev_b32_e32 v146, 16, v230
	v_and_b32_e32 v147, 0xffff0000, v230
	v_lshlrev_b32_e32 v148, 16, v231
	v_and_b32_e32 v149, 0xffff0000, v231
	v_lshlrev_b32_e32 v150, 16, v232
	v_and_b32_e32 v151, 0xffff0000, v232
	v_lshlrev_b32_e32 v166, 16, v233
	v_and_b32_e32 v167, 0xffff0000, v233
	v_mul_f32_e32 v22, v22, v146
	v_mul_f32_e32 v23, v23, v147
	v_mul_f32_e32 v24, v24, v148
	v_mul_f32_e32 v25, v25, v149
	v_mul_f32_e32 v18, v18, v150
	v_mul_f32_e32 v19, v19, v151
	v_mul_f32_e32 v20, v20, v166
	v_mul_f32_e32 v21, v21, v167
	v_cvt_pk_bf16_f32 v142, v22, v23
	v_cvt_pk_bf16_f32 v143, v24, v25
	v_cvt_pk_bf16_f32 v144, v18, v19
	v_cvt_pk_bf16_f32 v145, v20, v21
	global_store_dwordx4 v[182:183], v[142:145], off offset:1280
	v_lshl_add_u64 v[182:183], v[182:183], 0, v[178:179]
	v_fmamk_f32 v14, v14, 0xbfb8aa3b, v170
	v_fmamk_f32 v15, v15, 0xbfb8aa3b, v171
	v_fmamk_f32 v16, v16, 0xbfb8aa3b, v172
	v_fmamk_f32 v17, v17, 0xbfb8aa3b, v173
	v_fmamk_f32 v10, v10, 0xbfb8aa3b, v174
	v_fmamk_f32 v11, v11, 0xbfb8aa3b, v175
	v_fmamk_f32 v12, v12, 0xbfb8aa3b, v176
	v_fmamk_f32 v13, v13, 0xbfb8aa3b, v177
	v_exp_f32_e32 v14, v14
	v_exp_f32_e32 v15, v15
	v_exp_f32_e32 v16, v16
	v_exp_f32_e32 v17, v17
	v_exp_f32_e32 v10, v10
	v_exp_f32_e32 v11, v11
	v_exp_f32_e32 v12, v12
	v_exp_f32_e32 v13, v13
	v_add_f32_e32 v14, 1.0, v14
	v_add_f32_e32 v15, 1.0, v15
	v_add_f32_e32 v16, 1.0, v16
	v_add_f32_e32 v17, 1.0, v17
	v_add_f32_e32 v10, 1.0, v10
	v_add_f32_e32 v11, 1.0, v11
	v_add_f32_e32 v12, 1.0, v12
	v_add_f32_e32 v13, 1.0, v13
	v_rcp_f32_e32 v14, v14
	v_rcp_f32_e32 v15, v15
	v_rcp_f32_e32 v16, v16
	v_rcp_f32_e32 v17, v17
	v_rcp_f32_e32 v10, v10
	v_rcp_f32_e32 v11, v11
	v_rcp_f32_e32 v12, v12
	v_rcp_f32_e32 v13, v13
	s_waitcnt vmcnt(9)
; __device__ __forceinline__ unsigned cvt_pk_bf16(float lo, float hi) { unsigned r; asm volatile("v_cvt_pk_bf16_f32 %0, %1, %2" : "=v"(r) : "v"(lo), "v"(hi)); return r; }
; __device__ __forceinline__ float bflo(unsigned w) { return __uint_as_float(w << 16); }
; __device__ __forceinline__ float bfhi(unsigned w) { return __uint_as_float(w & 0xffff0000u); }
; __device__ __forceinline__ float sigm(float v) { return frcp(1.f + fexp2(-LOG2E * v)); }
;     __device__ __forceinline__ void operator()(const f32x4 (&acc)[2][2][4][2], const Unit& u, int wr, int wc, int fr, int fq) const {
;     ...
;         for (int bj = 0; bj < 2; ++bj) {
;             const int col = u.pn * 256 + bj * 128 + c8;
;             const f32x4 b0 = *(const f32x4*)(b_glu + col), b1 = *(const f32x4*)(b_glu + col + 4);
; #pragma unroll
;             for (int ai = 0; ai < 2; ++ai)
; #pragma unroll
;                 for (int m = 0; m < 4; ++m) {
;                     const size_t row = (size_t)(row0 + ai * 128 + m * 16);
;                     const v4u y = __builtin_nontemporal_load((const v4u*)(YG + row * 512 + col)), z = __builtin_nontemporal_load((const v4u*)(ZS + row * 512 + col));
;                     const f32x4 a0 = acc[ai][bj][m][0], a1 = acc[ai][bj][m][1];
;                     v4u w;
;                     w.x = pg8::cvt_pk_bf16(bflo(y.x) * sigm(a0[0] + b0[0]) * bflo(z.x), bfhi(y.x) * sigm(a0[1] + b0[1]) * bfhi(z.x));
;                     w.y = pg8::cvt_pk_bf16(bflo(y.y) * sigm(a0[2] + b0[2]) * bflo(z.y), bfhi(y.y) * sigm(a0[3] + b0[3]) * bfhi(z.y));
;                     w.z = pg8::cvt_pk_bf16(bflo(y.z) * sigm(a1[0] + b1[0]) * bflo(z.z), bfhi(y.z) * sigm(a1[1] + b1[1]) * bfhi(z.z));
;                     w.w = pg8::cvt_pk_bf16(bflo(y.w) * sigm(a1[2] + b1[2]) * bflo(z.w), bfhi(y.w) * sigm(a1[3] + b1[3]) * bfhi(z.w));
;                     *(v4u*)(A5 + row * 1024 + 512 + col) = w;
;                 }
;         }
	v_lshlrev_b32_e32 v146, 16, v234
	v_and_b32_e32 v147, 0xffff0000, v234
	v_lshlrev_b32_e32 v148, 16, v235
	v_and_b32_e32 v149, 0xffff0000, v235
	v_lshlrev_b32_e32 v150, 16, v236
	v_and_b32_e32 v151, 0xffff0000, v236
	v_lshlrev_b32_e32 v166, 16, v237
	v_and_b32_e32 v167, 0xffff0000, v237
	v_mul_f32_e32 v14, v14, v146
	v_mul_f32_e32 v15, v15, v147
	v_mul_f32_e32 v16, v16, v148
	v_mul_f32_e32 v17, v17, v149
	v_mul_f32_e32 v10, v10, v150
	v_mul_f32_e32 v11, v11, v151
	v_mul_f32_e32 v12, v12, v166
	v_mul_f32_e32 v13, v13, v167
	v_lshlrev_b32_e32 v146, 16, v238
	v_and_b32_e32 v147, 0xffff0000, v238
	v_lshlrev_b32_e32 v148, 16, v239
	v_and_b32_e32 v149, 0xffff0000, v239
	v_lshlrev_b32_e32 v150, 16, v240
	v_and_b32_e32 v151, 0xffff0000, v240
	v_lshlrev_b32_e32 v166, 16, v241
	v_and_b32_e32 v167, 0xffff0000, v241
	v_mul_f32_e32 v14, v14, v146
	v_mul_f32_e32 v15, v15, v147
	v_mul_f32_e32 v16, v16, v148
	v_mul_f32_e32 v17, v17, v149
	v_mul_f32_e32 v10, v10, v150
	v_mul_f32_e32 v11, v11, v151
	v_mul_f32_e32 v12, v12, v166
	v_mul_f32_e32 v13, v13, v167
	v_cvt_pk_bf16_f32 v138, v14, v15
	v_cvt_pk_bf16_f32 v139, v16, v17
	v_cvt_pk_bf16_f32 v140, v10, v11
	v_cvt_pk_bf16_f32 v141, v12, v13
	global_store_dwordx4 v[182:183], v[138:141], off offset:1280
	v_lshl_add_u64 v[182:183], v[182:183], 0, v[178:179]
	v_fmamk_f32 v6, v6, 0xbfb8aa3b, v170
	v_fmamk_f32 v7, v7, 0xbfb8aa3b, v171
	v_fmamk_f32 v8, v8, 0xbfb8aa3b, v172
	v_fmamk_f32 v9, v9, 0xbfb8aa3b, v173
	v_fmamk_f32 v2, v2, 0xbfb8aa3b, v174
	v_fmamk_f32 v3, v3, 0xbfb8aa3b, v175
	v_fmamk_f32 v4, v4, 0xbfb8aa3b, v176
	v_fmamk_f32 v5, v5, 0xbfb8aa3b, v177
	v_exp_f32_e32 v6, v6
	v_exp_f32_e32 v7, v7
	v_exp_f32_e32 v8, v8
	v_exp_f32_e32 v9, v9
	v_exp_f32_e32 v2, v2
	v_exp_f32_e32 v3, v3
	v_exp_f32_e32 v4, v4
	v_exp_f32_e32 v5, v5
	v_add_f32_e32 v6, 1.0, v6
	v_add_f32_e32 v7, 1.0, v7
	v_add_f32_e32 v8, 1.0, v8
	v_add_f32_e32 v9, 1.0, v9
	v_add_f32_e32 v2, 1.0, v2
	v_add_f32_e32 v3, 1.0, v3
	v_add_f32_e32 v4, 1.0, v4
	v_add_f32_e32 v5, 1.0, v5
	v_rcp_f32_e32 v6, v6
	v_rcp_f32_e32 v7, v7
	v_rcp_f32_e32 v8, v8
	v_rcp_f32_e32 v9, v9
	v_rcp_f32_e32 v2, v2
	v_rcp_f32_e32 v3, v3
	v_rcp_f32_e32 v4, v4
	v_rcp_f32_e32 v5, v5
	s_waitcnt vmcnt(7)
	v_lshlrev_b32_e32 v146, 16, v242
	v_and_b32_e32 v147, 0xffff0000, v242
	v_lshlrev_b32_e32 v148, 16, v243
	v_and_b32_e32 v149, 0xffff0000, v243
	v_lshlrev_b32_e32 v150, 16, v244
	v_and_b32_e32 v151, 0xffff0000, v244
	v_lshlrev_b32_e32 v166, 16, v245
	v_and_b32_e32 v167, 0xffff0000, v245
	v_mul_f32_e32 v6, v6, v146
	v_mul_f32_e32 v7, v7, v147
	v_mul_f32_e32 v8, v8, v148
	v_mul_f32_e32 v9, v9, v149
	v_mul_f32_e32 v2, v2, v150
	v_mul_f32_e32 v3, v3, v151
	v_mul_f32_e32 v4, v4, v166
	v_mul_f32_e32 v5, v5, v167
	v_lshlrev_b32_e32 v146, 16, v246
	v_and_b32_e32 v147, 0xffff0000, v246
	v_lshlrev_b32_e32 v148, 16, v247
	v_and_b32_e32 v149, 0xffff0000, v247
	v_lshlrev_b32_e32 v150, 16, v248
	v_and_b32_e32 v151, 0xffff0000, v248
	v_lshlrev_b32_e32 v166, 16, v249
	v_and_b32_e32 v167, 0xffff0000, v249
	v_mul_f32_e32 v6, v6, v146
	v_mul_f32_e32 v7, v7, v147
	v_mul_f32_e32 v8, v8, v148
	v_mul_f32_e32 v9, v9, v149
	v_mul_f32_e32 v2, v2, v150
	v_mul_f32_e32 v3, v3, v151
	v_mul_f32_e32 v4, v4, v166
	v_mul_f32_e32 v5, v5, v167
	v_cvt_pk_bf16_f32 v142, v6, v7
	v_cvt_pk_bf16_f32 v143, v8, v9
	v_cvt_pk_bf16_f32 v144, v2, v3
	v_cvt_pk_bf16_f32 v145, v4, v5
	global_store_dwordx4 v[182:183], v[142:145], off offset:1280
	s_cbranch_vccnz .LBB0_655
	s_andn2_b64 vcc, exec, s[4:5]
	s_cbranch_vccnz .LBB0_654
	s_barrier
	s_branch .LBB0_654
